# dn_prep forward substitution (I+A)^-1 spread over all 8 waves (blocked by 8, DPP partial sums) instead of wave 0 only; f32 as before
# speedup vs baseline: 1.0257x; 1.0257x over previous
; #define LAS __attribute__((address_space(3)))
; __device__ __forceinline__ bf16_t f2bf(float f) { return (bf16_t)(cvt_pk_bf16(f, 0.f) & 0xffffu); }
; __device__ __forceinline__ void dn_prep(const Params& p, LAS unsigned char* lds) {
;     ...
;         if (wid == 0) {
;             float T[64];
;             int zoff; asm volatile("v_mov_b32 %0, 0" : "=v"(zoff));
;             const LAS float* Asz = As + zoff;
;             const float bc = beta_s[lane], wcf = bc * __expf(G_s[lane]);
;             int lo2 = lane; asm volatile("" : "+v"(lo2));
;             LAS bf16_t* tub = Tu + lo2; LAS bf16_t* twb = Tw + lo2;
;             f32x4 rlo[2][8], rhi[8];
;             T[0] = (lane == 0) ? 1.f : 0.f;
;             tub[0] = f2bf(T[0] * bc); twb[0] = f2bf(T[0] * wcf);
;             rlo[1][0] = *(const LAS f32x4*)(Asz + 68);
; #pragma unroll
;             for (int i = 1; i < 64; ++i) {
; #pragma unroll
;                 for (int j4 = 8; j4 < (i + 3) / 4; ++j4) rhi[j4 - 8] = *(const LAS f32x4*)(Asz + i * 68 + j4 * 4);
;                 if (i + 1 < 64) {
; #pragma unroll
;                     for (int j4 = 0; j4 < ((i + 4) / 4 < 8 ? (i + 4) / 4 : 8); ++j4) rlo[(i + 1) & 1][j4] = *(const LAS f32x4*)(Asz + (i + 1) * 68 + j4 * 4);
;                 }
;                 float a0 = (lane == i) ? 1.f : 0.f, a1 = 0.f, a2 = 0.f, a3 = 0.f;
; #pragma unroll
;                 for (int j4 = 0; j4 < (i + 3) / 4; ++j4) {
;                     const f32x4 av = (j4 < 8) ? rlo[i & 1][j4 & 7] : rhi[(j4 - 8) & 7];
;                     if (j4 * 4 + 0 < i) a0 -= av[0] * T[j4 * 4 + 0];
;                     if (j4 * 4 + 1 < i) a1 -= av[1] * T[j4 * 4 + 1];
;                     if (j4 * 4 + 2 < i) a2 -= av[2] * T[j4 * 4 + 2];
;                     if (j4 * 4 + 3 < i) a3 -= av[3] * T[j4 * 4 + 3];
;                 }
;                 T[i] = (a0 + a1) + (a2 + a3);
;                 tub[i * 72] = f2bf(T[i] * bc); twb[i * 72] = f2bf(T[i] * wcf);
;                 __builtin_amdgcn_sched_barrier(0);
;             }
;         }
.LBB0_375:
	s_or_b64 exec, exec, s[24:25]
	s_waitcnt lgkmcnt(0)
	s_barrier
	s_and_b64 s[0:1], s[2:3], s[68:69]
	s_xor_b64 s[0:1], s[0:1], -1
	s_and_saveexec_b64 s[6:7], s[0:1]
	s_xor_b64 s[24:25], exec, s[6:7]
	s_cbranch_execz .LBB0_379
	s_mov_b64 s[28:29], exec
	s_and_b64 vcc, exec, s[68:69]
	s_cbranch_vccnz .LBB0_378
	v_readfirstlane_b32 s1, v184
	v_and_b32_e32 v7, 63, v184
	s_nop 3
	s_lshr_b32 s1, s1, 6
	v_and_b32_e32 v6, 7, v7
	v_lshrrev_b32_e32 v7, 3, v7
	s_lshl_b32 s32, s1, 3
	s_movk_i32 s89, 0x90
	s_mov_b32 s6, 0x02020202
	s_mov_b32 s7, 0x02020202
	s_mov_b32 s68, 0x04040404
	s_mov_b32 s69, 0x04040404
	s_mov_b32 s92, 0x08080808
	s_mov_b32 s93, 0x08080808
	s_mov_b32 s94, 0x10101010
	s_mov_b32 s95, 0x10101010
	s_mov_b32 s96, 0x20202020
	s_mov_b32 s97, 0x20202020
	s_mov_b32 s98, 0x40404040
	s_mov_b32 s99, 0x40404040
	s_mov_b32 s100, 0x80808080
	s_mov_b32 s101, 0x80808080
	v_add_u32_e32 v128, s32, v7
	v_cmp_eq_u32_e32 vcc, 0, v7
	s_nop 1
	v_cndmask_b32_e64 v16, 0, 1.0, vcc
	v_cmp_eq_u32_e32 vcc, 1, v7
	s_nop 1
	v_cndmask_b32_e64 v17, 0, 1.0, vcc
	v_cmp_eq_u32_e32 vcc, 2, v7
	s_nop 1
	v_cndmask_b32_e64 v18, 0, 1.0, vcc
	v_cmp_eq_u32_e32 vcc, 3, v7
	s_nop 1
	v_cndmask_b32_e64 v19, 0, 1.0, vcc
	v_cmp_eq_u32_e32 vcc, 4, v7
	s_nop 1
	v_cndmask_b32_e64 v20, 0, 1.0, vcc
	v_cmp_eq_u32_e32 vcc, 5, v7
	s_nop 1
	v_cndmask_b32_e64 v21, 0, 1.0, vcc
	v_cmp_eq_u32_e32 vcc, 6, v7
	s_nop 1
	v_cndmask_b32_e64 v22, 0, 1.0, vcc
	v_cmp_eq_u32_e32 vcc, 7, v7
	s_nop 1
	v_cndmask_b32_e64 v23, 0, 1.0, vcc
	v_lshl_add_u32 v0, v6, 2, s13
	v_mov_b32_e32 v1, s13
	v_lshlrev_b32_e32 v2, 1, v128
	v_mad_u32_u24 v2, v6, s89, v2
	v_add_u32_e32 v3, 0x18000, v2
	v_add_u32_e32 v2, 0x15c00, v2
	v_lshlrev_b32_e32 v129, 2, v128
	v_add_u32_e32 v129, 0x1a400, v129
	ds_read_b32 v4, v129
	ds_read_b32 v5, v129 offset:256
	ds_read_b128 v[32:35], v1 offset:272
	ds_read_b128 v[36:39], v1 offset:544
	ds_read_b128 v[40:43], v1 offset:816
	ds_read_b128 v[44:47], v1 offset:1088
	ds_read_b128 v[48:51], v1 offset:1360
	ds_read_b128 v[52:55], v1 offset:1376
	ds_read_b128 v[56:59], v1 offset:1632
	ds_read_b128 v[60:63], v1 offset:1648
	ds_read_b128 v[64:67], v1 offset:1904
	ds_read_b128 v[68:71], v1 offset:1920
	v_mov_b32_e32 v8, 0
	v_mov_b32_e32 v9, 0
	v_mov_b32_e32 v10, 0
	v_mov_b32_e32 v11, 0
	v_mov_b32_e32 v12, 0
	v_mov_b32_e32 v13, 0
	v_mov_b32_e32 v14, 0
	v_mov_b32_e32 v15, 0
	v_mov_b32_e32 v6, 0
	s_mov_b32 s91, 1.0
	s_waitcnt lgkmcnt(10)
	v_mul_f32_e32 v5, 0x3fb8aa3b, v5
	v_exp_f32_e32 v5, v5
	s_nop 0
	v_mul_f32_e32 v5, v4, v5
.Lfs_b0:
	s_cmp_gt_u32 s1, 0
	s_cbranch_scc1 .Lfs_z0
	v_mul_f32_e32 v24, s91, v16
	v_mul_f32_e32 v25, s91, v17
	v_mul_f32_e32 v26, s91, v18
	v_mul_f32_e32 v27, s91, v19
	v_mul_f32_e32 v28, s91, v20
	v_mul_f32_e32 v29, s91, v21
	v_mul_f32_e32 v30, s91, v22
	v_mul_f32_e32 v31, s91, v23
	s_waitcnt lgkmcnt(0)
	ds_read_b32 v72, v0 offset:2176
	ds_read_b32 v79, v0 offset:2448
	ds_read_b32 v86, v0 offset:2720
	ds_read_b32 v93, v0 offset:2992
	ds_read_b32 v100, v0 offset:3264
	ds_read_b32 v107, v0 offset:3536
	ds_read_b32 v114, v0 offset:3808
	ds_read_b32 v121, v0 offset:4080
	v_fma_f32 v25, -v32, v24, v25
	v_fma_f32 v26, -v36, v24, v26
	v_fma_f32 v27, -v40, v24, v27
	v_fma_f32 v28, -v44, v24, v28
	v_fma_f32 v29, -v48, v24, v29
	v_fma_f32 v30, -v56, v24, v30
	v_fma_f32 v31, -v64, v24, v31
	v_fma_f32 v26, -v37, v25, v26
	v_fma_f32 v27, -v41, v25, v27
	v_fma_f32 v28, -v45, v25, v28
	v_fma_f32 v29, -v49, v25, v29
	v_fma_f32 v30, -v57, v25, v30
	v_fma_f32 v31, -v65, v25, v31
	v_fma_f32 v27, -v42, v26, v27
	v_fma_f32 v28, -v46, v26, v28
	v_fma_f32 v29, -v50, v26, v29
	v_fma_f32 v30, -v58, v26, v30
	v_fma_f32 v31, -v66, v26, v31
	v_fma_f32 v28, -v47, v27, v28
	v_fma_f32 v29, -v51, v27, v29
	v_fma_f32 v30, -v59, v27, v30
	v_fma_f32 v31, -v67, v27, v31
	v_fma_f32 v29, -v52, v28, v29
	v_fma_f32 v30, -v60, v28, v30
	v_fma_f32 v31, -v68, v28, v31
	v_fma_f32 v30, -v61, v29, v30
	v_fma_f32 v31, -v69, v29, v31
	v_fma_f32 v31, -v70, v30, v31
	ds_read_b128 v[32:35], v1 offset:2480
	ds_read_b128 v[36:39], v1 offset:2752
	ds_read_b128 v[40:43], v1 offset:3024
	ds_read_b128 v[44:47], v1 offset:3296
	ds_read_b128 v[48:51], v1 offset:3568
	ds_read_b128 v[52:55], v1 offset:3584
	ds_read_b128 v[56:59], v1 offset:3840
	ds_read_b128 v[60:63], v1 offset:3856
	ds_read_b128 v[64:67], v1 offset:4112
	ds_read_b128 v[68:71], v1 offset:4128
	v_mov_b32_e32 v8, v24
	v_cndmask_b32_e64 v8, v8, v25, s[6:7]
	v_cndmask_b32_e64 v8, v8, v26, s[68:69]
	v_cndmask_b32_e64 v8, v8, v27, s[92:93]
	v_cndmask_b32_e64 v8, v8, v28, s[94:95]
	v_cndmask_b32_e64 v8, v8, v29, s[96:97]
	v_cndmask_b32_e64 v8, v8, v30, s[98:99]
	v_cndmask_b32_e64 v8, v8, v31, s[100:101]
	v_mul_f32_e32 v128, v4, v8
	v_mul_f32_e32 v129, v5, v8
	v_cvt_pk_bf16_f32 v128, v128, v128
	v_cvt_pk_bf16_f32 v129, v129, v129
	ds_write_b16 v2, v128 offset:0
	ds_write_b16 v3, v129 offset:0
	s_mov_b32 s91, 0
; #define LAS __attribute__((address_space(3)))
; __device__ __forceinline__ bf16_t f2bf(float f) { return (bf16_t)(cvt_pk_bf16(f, 0.f) & 0xffffu); }
; __device__ __forceinline__ void dn_prep(const Params& p, LAS unsigned char* lds) {
;     ...
;             for (int i = 1; i < 64; ++i) {
; #pragma unroll
;                 for (int j4 = 8; j4 < (i + 3) / 4; ++j4) rhi[j4 - 8] = *(const LAS f32x4*)(Asz + i * 68 + j4 * 4);
;                 if (i + 1 < 64) {
; #pragma unroll
;                     for (int j4 = 0; j4 < ((i + 4) / 4 < 8 ? (i + 4) / 4 : 8); ++j4) rlo[(i + 1) & 1][j4] = *(const LAS f32x4*)(Asz + (i + 1) * 68 + j4 * 4);
;                 }
;                 float a0 = (lane == i) ? 1.f : 0.f, a1 = 0.f, a2 = 0.f, a3 = 0.f;
; #pragma unroll
;                 for (int j4 = 0; j4 < (i + 3) / 4; ++j4) {
;                     const f32x4 av = (j4 < 8) ? rlo[i & 1][j4 & 7] : rhi[(j4 - 8) & 7];
;                     if (j4 * 4 + 0 < i) a0 -= av[0] * T[j4 * 4 + 0];
;                     if (j4 * 4 + 1 < i) a1 -= av[1] * T[j4 * 4 + 1];
;                     if (j4 * 4 + 2 < i) a2 -= av[2] * T[j4 * 4 + 2];
;                     if (j4 * 4 + 3 < i) a3 -= av[3] * T[j4 * 4 + 3];
;                 }
;                 T[i] = (a0 + a1) + (a2 + a3);
;                 tub[i * 72] = f2bf(T[i] * bc); twb[i * 72] = f2bf(T[i] * wcf);
.Lfs_b1:
	s_cmp_gt_u32 s1, 1
	s_cbranch_scc1 .Lfs_z1
	s_waitcnt lgkmcnt(12)
	v_mul_f32_e32 v24, v72, v8
	v_mul_f32_e32 v25, v79, v8
	v_mul_f32_e32 v26, v86, v8
	v_mul_f32_e32 v27, v93, v8
	v_mul_f32_e32 v28, v100, v8
	v_mul_f32_e32 v29, v107, v8
	v_mul_f32_e32 v30, v114, v8
	v_mul_f32_e32 v31, v121, v8
	v_add_f32_dpp v24, v24, v24 quad_perm:[1,0,3,2] row_mask:0xf bank_mask:0xf bound_ctrl:1
	v_add_f32_dpp v25, v25, v25 quad_perm:[1,0,3,2] row_mask:0xf bank_mask:0xf bound_ctrl:1
	v_add_f32_dpp v26, v26, v26 quad_perm:[1,0,3,2] row_mask:0xf bank_mask:0xf bound_ctrl:1
	v_add_f32_dpp v27, v27, v27 quad_perm:[1,0,3,2] row_mask:0xf bank_mask:0xf bound_ctrl:1
	v_add_f32_dpp v28, v28, v28 quad_perm:[1,0,3,2] row_mask:0xf bank_mask:0xf bound_ctrl:1
	v_add_f32_dpp v29, v29, v29 quad_perm:[1,0,3,2] row_mask:0xf bank_mask:0xf bound_ctrl:1
	v_add_f32_dpp v30, v30, v30 quad_perm:[1,0,3,2] row_mask:0xf bank_mask:0xf bound_ctrl:1
	v_add_f32_dpp v31, v31, v31 quad_perm:[1,0,3,2] row_mask:0xf bank_mask:0xf bound_ctrl:1
	v_add_f32_dpp v24, v24, v24 quad_perm:[2,3,0,1] row_mask:0xf bank_mask:0xf bound_ctrl:1
	v_add_f32_dpp v25, v25, v25 quad_perm:[2,3,0,1] row_mask:0xf bank_mask:0xf bound_ctrl:1
	v_add_f32_dpp v26, v26, v26 quad_perm:[2,3,0,1] row_mask:0xf bank_mask:0xf bound_ctrl:1
	v_add_f32_dpp v27, v27, v27 quad_perm:[2,3,0,1] row_mask:0xf bank_mask:0xf bound_ctrl:1
	v_add_f32_dpp v28, v28, v28 quad_perm:[2,3,0,1] row_mask:0xf bank_mask:0xf bound_ctrl:1
	v_add_f32_dpp v29, v29, v29 quad_perm:[2,3,0,1] row_mask:0xf bank_mask:0xf bound_ctrl:1
	v_add_f32_dpp v30, v30, v30 quad_perm:[2,3,0,1] row_mask:0xf bank_mask:0xf bound_ctrl:1
	v_add_f32_dpp v31, v31, v31 quad_perm:[2,3,0,1] row_mask:0xf bank_mask:0xf bound_ctrl:1
	v_add_f32_dpp v24, v24, v24 row_half_mirror row_mask:0xf bank_mask:0xf bound_ctrl:1
	v_add_f32_dpp v25, v25, v25 row_half_mirror row_mask:0xf bank_mask:0xf bound_ctrl:1
	v_add_f32_dpp v26, v26, v26 row_half_mirror row_mask:0xf bank_mask:0xf bound_ctrl:1
	v_add_f32_dpp v27, v27, v27 row_half_mirror row_mask:0xf bank_mask:0xf bound_ctrl:1
	v_add_f32_dpp v28, v28, v28 row_half_mirror row_mask:0xf bank_mask:0xf bound_ctrl:1
	v_add_f32_dpp v29, v29, v29 row_half_mirror row_mask:0xf bank_mask:0xf bound_ctrl:1
	v_add_f32_dpp v30, v30, v30 row_half_mirror row_mask:0xf bank_mask:0xf bound_ctrl:1
	v_add_f32_dpp v31, v31, v31 row_half_mirror row_mask:0xf bank_mask:0xf bound_ctrl:1
	v_fma_f32 v24, v16, s91, -v24
	v_fma_f32 v25, v17, s91, -v25
	v_fma_f32 v26, v18, s91, -v26
	v_fma_f32 v27, v19, s91, -v27
	v_fma_f32 v28, v20, s91, -v28
	v_fma_f32 v29, v21, s91, -v29
	v_fma_f32 v30, v22, s91, -v30
	v_fma_f32 v31, v23, s91, -v31
	s_waitcnt lgkmcnt(0)
	ds_read_b32 v72, v0 offset:4352
	ds_read_b32 v73, v0 offset:4384
	ds_read_b32 v79, v0 offset:4624
	ds_read_b32 v80, v0 offset:4656
	ds_read_b32 v86, v0 offset:4896
	ds_read_b32 v87, v0 offset:4928
	ds_read_b32 v93, v0 offset:5168
	ds_read_b32 v94, v0 offset:5200
	ds_read_b32 v100, v0 offset:5440
	ds_read_b32 v101, v0 offset:5472
	ds_read_b32 v107, v0 offset:5712
	ds_read_b32 v108, v0 offset:5744
	ds_read_b32 v114, v0 offset:5984
	ds_read_b32 v115, v0 offset:6016
	ds_read_b32 v121, v0 offset:6256
	ds_read_b32 v122, v0 offset:6288
	v_fma_f32 v25, -v32, v24, v25
	v_fma_f32 v26, -v36, v24, v26
	v_fma_f32 v27, -v40, v24, v27
	v_fma_f32 v28, -v44, v24, v28
	v_fma_f32 v29, -v48, v24, v29
	v_fma_f32 v30, -v56, v24, v30
	v_fma_f32 v31, -v64, v24, v31
	v_fma_f32 v26, -v37, v25, v26
	v_fma_f32 v27, -v41, v25, v27
	v_fma_f32 v28, -v45, v25, v28
	v_fma_f32 v29, -v49, v25, v29
	v_fma_f32 v30, -v57, v25, v30
	v_fma_f32 v31, -v65, v25, v31
	v_fma_f32 v27, -v42, v26, v27
	v_fma_f32 v28, -v46, v26, v28
	v_fma_f32 v29, -v50, v26, v29
	v_fma_f32 v30, -v58, v26, v30
	v_fma_f32 v31, -v66, v26, v31
	v_fma_f32 v28, -v47, v27, v28
	v_fma_f32 v29, -v51, v27, v29
	v_fma_f32 v30, -v59, v27, v30
	v_fma_f32 v31, -v67, v27, v31
	v_fma_f32 v29, -v52, v28, v29
	v_fma_f32 v30, -v60, v28, v30
	v_fma_f32 v31, -v68, v28, v31
	v_fma_f32 v30, -v61, v29, v30
	v_fma_f32 v31, -v69, v29, v31
	v_fma_f32 v31, -v70, v30, v31
	ds_read_b128 v[32:35], v1 offset:4688
	ds_read_b128 v[36:39], v1 offset:4960
	ds_read_b128 v[40:43], v1 offset:5232
	ds_read_b128 v[44:47], v1 offset:5504
	ds_read_b128 v[48:51], v1 offset:5776
	ds_read_b128 v[52:55], v1 offset:5792
	ds_read_b128 v[56:59], v1 offset:6048
	ds_read_b128 v[60:63], v1 offset:6064
	ds_read_b128 v[64:67], v1 offset:6320
	ds_read_b128 v[68:71], v1 offset:6336
	v_mov_b32_e32 v9, v24
	v_cndmask_b32_e64 v9, v9, v25, s[6:7]
	v_cndmask_b32_e64 v9, v9, v26, s[68:69]
	v_cndmask_b32_e64 v9, v9, v27, s[92:93]
	v_cndmask_b32_e64 v9, v9, v28, s[94:95]
	v_cndmask_b32_e64 v9, v9, v29, s[96:97]
	v_cndmask_b32_e64 v9, v9, v30, s[98:99]
	v_cndmask_b32_e64 v9, v9, v31, s[100:101]
	v_mul_f32_e32 v128, v4, v9
	v_mul_f32_e32 v129, v5, v9
	v_cvt_pk_bf16_f32 v128, v128, v128
	v_cvt_pk_bf16_f32 v129, v129, v129
	ds_write_b16 v2, v128 offset:1152
	ds_write_b16 v3, v129 offset:1152
	s_mov_b32 s91, 0
; #define LAS __attribute__((address_space(3)))
; __device__ __forceinline__ bf16_t f2bf(float f) { return (bf16_t)(cvt_pk_bf16(f, 0.f) & 0xffffu); }
; __device__ __forceinline__ void dn_prep(const Params& p, LAS unsigned char* lds) {
;     ...
;             for (int i = 1; i < 64; ++i) {
; #pragma unroll
;                 for (int j4 = 8; j4 < (i + 3) / 4; ++j4) rhi[j4 - 8] = *(const LAS f32x4*)(Asz + i * 68 + j4 * 4);
;                 if (i + 1 < 64) {
; #pragma unroll
;                     for (int j4 = 0; j4 < ((i + 4) / 4 < 8 ? (i + 4) / 4 : 8); ++j4) rlo[(i + 1) & 1][j4] = *(const LAS f32x4*)(Asz + (i + 1) * 68 + j4 * 4);
;                 }
;                 float a0 = (lane == i) ? 1.f : 0.f, a1 = 0.f, a2 = 0.f, a3 = 0.f;
; #pragma unroll
;                 for (int j4 = 0; j4 < (i + 3) / 4; ++j4) {
;                     const f32x4 av = (j4 < 8) ? rlo[i & 1][j4 & 7] : rhi[(j4 - 8) & 7];
;                     if (j4 * 4 + 0 < i) a0 -= av[0] * T[j4 * 4 + 0];
;                     if (j4 * 4 + 1 < i) a1 -= av[1] * T[j4 * 4 + 1];
;                     if (j4 * 4 + 2 < i) a2 -= av[2] * T[j4 * 4 + 2];
;                     if (j4 * 4 + 3 < i) a3 -= av[3] * T[j4 * 4 + 3];
;                 }
;                 T[i] = (a0 + a1) + (a2 + a3);
;                 tub[i * 72] = f2bf(T[i] * bc); twb[i * 72] = f2bf(T[i] * wcf);
.Lfs_b2:
	s_cmp_gt_u32 s1, 2
	s_cbranch_scc1 .Lfs_z2
	s_waitcnt lgkmcnt(12)
	v_mul_f32_e32 v24, v72, v8
	v_mul_f32_e32 v25, v79, v8
	v_mul_f32_e32 v26, v86, v8
	v_mul_f32_e32 v27, v93, v8
	v_mul_f32_e32 v28, v100, v8
	v_mul_f32_e32 v29, v107, v8
	v_mul_f32_e32 v30, v114, v8
	v_mul_f32_e32 v31, v121, v8
	v_fmac_f32_e32 v24, v73, v9
	v_fmac_f32_e32 v25, v80, v9
	v_fmac_f32_e32 v26, v87, v9
	v_fmac_f32_e32 v27, v94, v9
	v_fmac_f32_e32 v28, v101, v9
	v_fmac_f32_e32 v29, v108, v9
	v_fmac_f32_e32 v30, v115, v9
	v_fmac_f32_e32 v31, v122, v9
	v_add_f32_dpp v24, v24, v24 quad_perm:[1,0,3,2] row_mask:0xf bank_mask:0xf bound_ctrl:1
	v_add_f32_dpp v25, v25, v25 quad_perm:[1,0,3,2] row_mask:0xf bank_mask:0xf bound_ctrl:1
	v_add_f32_dpp v26, v26, v26 quad_perm:[1,0,3,2] row_mask:0xf bank_mask:0xf bound_ctrl:1
	v_add_f32_dpp v27, v27, v27 quad_perm:[1,0,3,2] row_mask:0xf bank_mask:0xf bound_ctrl:1
	v_add_f32_dpp v28, v28, v28 quad_perm:[1,0,3,2] row_mask:0xf bank_mask:0xf bound_ctrl:1
	v_add_f32_dpp v29, v29, v29 quad_perm:[1,0,3,2] row_mask:0xf bank_mask:0xf bound_ctrl:1
	v_add_f32_dpp v30, v30, v30 quad_perm:[1,0,3,2] row_mask:0xf bank_mask:0xf bound_ctrl:1
	v_add_f32_dpp v31, v31, v31 quad_perm:[1,0,3,2] row_mask:0xf bank_mask:0xf bound_ctrl:1
	v_add_f32_dpp v24, v24, v24 quad_perm:[2,3,0,1] row_mask:0xf bank_mask:0xf bound_ctrl:1
	v_add_f32_dpp v25, v25, v25 quad_perm:[2,3,0,1] row_mask:0xf bank_mask:0xf bound_ctrl:1
	v_add_f32_dpp v26, v26, v26 quad_perm:[2,3,0,1] row_mask:0xf bank_mask:0xf bound_ctrl:1
	v_add_f32_dpp v27, v27, v27 quad_perm:[2,3,0,1] row_mask:0xf bank_mask:0xf bound_ctrl:1
	v_add_f32_dpp v28, v28, v28 quad_perm:[2,3,0,1] row_mask:0xf bank_mask:0xf bound_ctrl:1
	v_add_f32_dpp v29, v29, v29 quad_perm:[2,3,0,1] row_mask:0xf bank_mask:0xf bound_ctrl:1
	v_add_f32_dpp v30, v30, v30 quad_perm:[2,3,0,1] row_mask:0xf bank_mask:0xf bound_ctrl:1
	v_add_f32_dpp v31, v31, v31 quad_perm:[2,3,0,1] row_mask:0xf bank_mask:0xf bound_ctrl:1
	v_add_f32_dpp v24, v24, v24 row_half_mirror row_mask:0xf bank_mask:0xf bound_ctrl:1
	v_add_f32_dpp v25, v25, v25 row_half_mirror row_mask:0xf bank_mask:0xf bound_ctrl:1
	v_add_f32_dpp v26, v26, v26 row_half_mirror row_mask:0xf bank_mask:0xf bound_ctrl:1
	v_add_f32_dpp v27, v27, v27 row_half_mirror row_mask:0xf bank_mask:0xf bound_ctrl:1
	v_add_f32_dpp v28, v28, v28 row_half_mirror row_mask:0xf bank_mask:0xf bound_ctrl:1
	v_add_f32_dpp v29, v29, v29 row_half_mirror row_mask:0xf bank_mask:0xf bound_ctrl:1
	v_add_f32_dpp v30, v30, v30 row_half_mirror row_mask:0xf bank_mask:0xf bound_ctrl:1
	v_add_f32_dpp v31, v31, v31 row_half_mirror row_mask:0xf bank_mask:0xf bound_ctrl:1
	v_fma_f32 v24, v16, s91, -v24
	v_fma_f32 v25, v17, s91, -v25
	v_fma_f32 v26, v18, s91, -v26
	v_fma_f32 v27, v19, s91, -v27
	v_fma_f32 v28, v20, s91, -v28
	v_fma_f32 v29, v21, s91, -v29
	v_fma_f32 v30, v22, s91, -v30
	v_fma_f32 v31, v23, s91, -v31
	s_waitcnt lgkmcnt(0)
	ds_read_b32 v72, v0 offset:6528
	ds_read_b32 v73, v0 offset:6560
	ds_read_b32 v74, v0 offset:6592
	ds_read_b32 v79, v0 offset:6800
	ds_read_b32 v80, v0 offset:6832
	ds_read_b32 v81, v0 offset:6864
	ds_read_b32 v86, v0 offset:7072
	ds_read_b32 v87, v0 offset:7104
	ds_read_b32 v88, v0 offset:7136
	ds_read_b32 v93, v0 offset:7344
	ds_read_b32 v94, v0 offset:7376
	ds_read_b32 v95, v0 offset:7408
	ds_read_b32 v100, v0 offset:7616
	ds_read_b32 v101, v0 offset:7648
	ds_read_b32 v102, v0 offset:7680
	ds_read_b32 v107, v0 offset:7888
	ds_read_b32 v108, v0 offset:7920
	ds_read_b32 v109, v0 offset:7952
	ds_read_b32 v114, v0 offset:8160
	ds_read_b32 v115, v0 offset:8192
	ds_read_b32 v116, v0 offset:8224
	ds_read_b32 v121, v0 offset:8432
	ds_read_b32 v122, v0 offset:8464
	ds_read_b32 v123, v0 offset:8496
	v_fma_f32 v25, -v32, v24, v25
	v_fma_f32 v26, -v36, v24, v26
	v_fma_f32 v27, -v40, v24, v27
	v_fma_f32 v28, -v44, v24, v28
	v_fma_f32 v29, -v48, v24, v29
	v_fma_f32 v30, -v56, v24, v30
	v_fma_f32 v31, -v64, v24, v31
	v_fma_f32 v26, -v37, v25, v26
	v_fma_f32 v27, -v41, v25, v27
	v_fma_f32 v28, -v45, v25, v28
	v_fma_f32 v29, -v49, v25, v29
	v_fma_f32 v30, -v57, v25, v30
	v_fma_f32 v31, -v65, v25, v31
	v_fma_f32 v27, -v42, v26, v27
	v_fma_f32 v28, -v46, v26, v28
	v_fma_f32 v29, -v50, v26, v29
	v_fma_f32 v30, -v58, v26, v30
	v_fma_f32 v31, -v66, v26, v31
	v_fma_f32 v28, -v47, v27, v28
	v_fma_f32 v29, -v51, v27, v29
	v_fma_f32 v30, -v59, v27, v30
	v_fma_f32 v31, -v67, v27, v31
	v_fma_f32 v29, -v52, v28, v29
	v_fma_f32 v30, -v60, v28, v30
	v_fma_f32 v31, -v68, v28, v31
	v_fma_f32 v30, -v61, v29, v30
	v_fma_f32 v31, -v69, v29, v31
	v_fma_f32 v31, -v70, v30, v31
	ds_read_b128 v[32:35], v1 offset:6896
	ds_read_b128 v[36:39], v1 offset:7168
	ds_read_b128 v[40:43], v1 offset:7440
	ds_read_b128 v[44:47], v1 offset:7712
	ds_read_b128 v[48:51], v1 offset:7984
	ds_read_b128 v[52:55], v1 offset:8000
	ds_read_b128 v[56:59], v1 offset:8256
	ds_read_b128 v[60:63], v1 offset:8272
	ds_read_b128 v[64:67], v1 offset:8528
	ds_read_b128 v[68:71], v1 offset:8544
	v_mov_b32_e32 v10, v24
	v_cndmask_b32_e64 v10, v10, v25, s[6:7]
	v_cndmask_b32_e64 v10, v10, v26, s[68:69]
	v_cndmask_b32_e64 v10, v10, v27, s[92:93]
	v_cndmask_b32_e64 v10, v10, v28, s[94:95]
	v_cndmask_b32_e64 v10, v10, v29, s[96:97]
	v_cndmask_b32_e64 v10, v10, v30, s[98:99]
	v_cndmask_b32_e64 v10, v10, v31, s[100:101]
	v_mul_f32_e32 v128, v4, v10
	v_mul_f32_e32 v129, v5, v10
	v_cvt_pk_bf16_f32 v128, v128, v128
	v_cvt_pk_bf16_f32 v129, v129, v129
	ds_write_b16 v2, v128 offset:2304
	ds_write_b16 v3, v129 offset:2304
	s_mov_b32 s91, 0
; #define LAS __attribute__((address_space(3)))
; __device__ __forceinline__ bf16_t f2bf(float f) { return (bf16_t)(cvt_pk_bf16(f, 0.f) & 0xffffu); }
; __device__ __forceinline__ void dn_prep(const Params& p, LAS unsigned char* lds) {
;     ...
;             for (int i = 1; i < 64; ++i) {
; #pragma unroll
;                 for (int j4 = 8; j4 < (i + 3) / 4; ++j4) rhi[j4 - 8] = *(const LAS f32x4*)(Asz + i * 68 + j4 * 4);
;                 if (i + 1 < 64) {
; #pragma unroll
;                     for (int j4 = 0; j4 < ((i + 4) / 4 < 8 ? (i + 4) / 4 : 8); ++j4) rlo[(i + 1) & 1][j4] = *(const LAS f32x4*)(Asz + (i + 1) * 68 + j4 * 4);
;                 }
;                 float a0 = (lane == i) ? 1.f : 0.f, a1 = 0.f, a2 = 0.f, a3 = 0.f;
; #pragma unroll
;                 for (int j4 = 0; j4 < (i + 3) / 4; ++j4) {
;                     const f32x4 av = (j4 < 8) ? rlo[i & 1][j4 & 7] : rhi[(j4 - 8) & 7];
;                     if (j4 * 4 + 0 < i) a0 -= av[0] * T[j4 * 4 + 0];
;                     if (j4 * 4 + 1 < i) a1 -= av[1] * T[j4 * 4 + 1];
;                     if (j4 * 4 + 2 < i) a2 -= av[2] * T[j4 * 4 + 2];
;                     if (j4 * 4 + 3 < i) a3 -= av[3] * T[j4 * 4 + 3];
;                 }
;                 T[i] = (a0 + a1) + (a2 + a3);
;                 tub[i * 72] = f2bf(T[i] * bc); twb[i * 72] = f2bf(T[i] * wcf);
.Lfs_b3:
	s_cmp_gt_u32 s1, 3
	s_cbranch_scc1 .Lfs_z3
	s_waitcnt lgkmcnt(12)
	v_mul_f32_e32 v24, v72, v8
	v_mul_f32_e32 v25, v79, v8
	v_mul_f32_e32 v26, v86, v8
	v_mul_f32_e32 v27, v93, v8
	v_mul_f32_e32 v28, v100, v8
	v_mul_f32_e32 v29, v107, v8
	v_mul_f32_e32 v30, v114, v8
	v_mul_f32_e32 v31, v121, v8
	v_fmac_f32_e32 v24, v73, v9
	v_fmac_f32_e32 v25, v80, v9
	v_fmac_f32_e32 v26, v87, v9
	v_fmac_f32_e32 v27, v94, v9
	v_fmac_f32_e32 v28, v101, v9
	v_fmac_f32_e32 v29, v108, v9
	v_fmac_f32_e32 v30, v115, v9
	v_fmac_f32_e32 v31, v122, v9
	v_fmac_f32_e32 v24, v74, v10
	v_fmac_f32_e32 v25, v81, v10
	v_fmac_f32_e32 v26, v88, v10
	v_fmac_f32_e32 v27, v95, v10
	v_fmac_f32_e32 v28, v102, v10
	v_fmac_f32_e32 v29, v109, v10
	v_fmac_f32_e32 v30, v116, v10
	v_fmac_f32_e32 v31, v123, v10
	v_add_f32_dpp v24, v24, v24 quad_perm:[1,0,3,2] row_mask:0xf bank_mask:0xf bound_ctrl:1
	v_add_f32_dpp v25, v25, v25 quad_perm:[1,0,3,2] row_mask:0xf bank_mask:0xf bound_ctrl:1
	v_add_f32_dpp v26, v26, v26 quad_perm:[1,0,3,2] row_mask:0xf bank_mask:0xf bound_ctrl:1
	v_add_f32_dpp v27, v27, v27 quad_perm:[1,0,3,2] row_mask:0xf bank_mask:0xf bound_ctrl:1
	v_add_f32_dpp v28, v28, v28 quad_perm:[1,0,3,2] row_mask:0xf bank_mask:0xf bound_ctrl:1
	v_add_f32_dpp v29, v29, v29 quad_perm:[1,0,3,2] row_mask:0xf bank_mask:0xf bound_ctrl:1
	v_add_f32_dpp v30, v30, v30 quad_perm:[1,0,3,2] row_mask:0xf bank_mask:0xf bound_ctrl:1
	v_add_f32_dpp v31, v31, v31 quad_perm:[1,0,3,2] row_mask:0xf bank_mask:0xf bound_ctrl:1
	v_add_f32_dpp v24, v24, v24 quad_perm:[2,3,0,1] row_mask:0xf bank_mask:0xf bound_ctrl:1
	v_add_f32_dpp v25, v25, v25 quad_perm:[2,3,0,1] row_mask:0xf bank_mask:0xf bound_ctrl:1
	v_add_f32_dpp v26, v26, v26 quad_perm:[2,3,0,1] row_mask:0xf bank_mask:0xf bound_ctrl:1
	v_add_f32_dpp v27, v27, v27 quad_perm:[2,3,0,1] row_mask:0xf bank_mask:0xf bound_ctrl:1
	v_add_f32_dpp v28, v28, v28 quad_perm:[2,3,0,1] row_mask:0xf bank_mask:0xf bound_ctrl:1
	v_add_f32_dpp v29, v29, v29 quad_perm:[2,3,0,1] row_mask:0xf bank_mask:0xf bound_ctrl:1
	v_add_f32_dpp v30, v30, v30 quad_perm:[2,3,0,1] row_mask:0xf bank_mask:0xf bound_ctrl:1
	v_add_f32_dpp v31, v31, v31 quad_perm:[2,3,0,1] row_mask:0xf bank_mask:0xf bound_ctrl:1
	v_add_f32_dpp v24, v24, v24 row_half_mirror row_mask:0xf bank_mask:0xf bound_ctrl:1
	v_add_f32_dpp v25, v25, v25 row_half_mirror row_mask:0xf bank_mask:0xf bound_ctrl:1
	v_add_f32_dpp v26, v26, v26 row_half_mirror row_mask:0xf bank_mask:0xf bound_ctrl:1
	v_add_f32_dpp v27, v27, v27 row_half_mirror row_mask:0xf bank_mask:0xf bound_ctrl:1
	v_add_f32_dpp v28, v28, v28 row_half_mirror row_mask:0xf bank_mask:0xf bound_ctrl:1
	v_add_f32_dpp v29, v29, v29 row_half_mirror row_mask:0xf bank_mask:0xf bound_ctrl:1
	v_add_f32_dpp v30, v30, v30 row_half_mirror row_mask:0xf bank_mask:0xf bound_ctrl:1
	v_add_f32_dpp v31, v31, v31 row_half_mirror row_mask:0xf bank_mask:0xf bound_ctrl:1
	v_fma_f32 v24, v16, s91, -v24
	v_fma_f32 v25, v17, s91, -v25
	v_fma_f32 v26, v18, s91, -v26
	v_fma_f32 v27, v19, s91, -v27
	v_fma_f32 v28, v20, s91, -v28
	v_fma_f32 v29, v21, s91, -v29
	v_fma_f32 v30, v22, s91, -v30
	v_fma_f32 v31, v23, s91, -v31
	s_waitcnt lgkmcnt(0)
	ds_read_b32 v72, v0 offset:8704
	ds_read_b32 v73, v0 offset:8736
	ds_read_b32 v74, v0 offset:8768
	ds_read_b32 v75, v0 offset:8800
	ds_read_b32 v79, v0 offset:8976
	ds_read_b32 v80, v0 offset:9008
	ds_read_b32 v81, v0 offset:9040
	ds_read_b32 v82, v0 offset:9072
	ds_read_b32 v86, v0 offset:9248
	ds_read_b32 v87, v0 offset:9280
	ds_read_b32 v88, v0 offset:9312
	ds_read_b32 v89, v0 offset:9344
	ds_read_b32 v93, v0 offset:9520
	ds_read_b32 v94, v0 offset:9552
	ds_read_b32 v95, v0 offset:9584
	ds_read_b32 v96, v0 offset:9616
	ds_read_b32 v100, v0 offset:9792
	ds_read_b32 v101, v0 offset:9824
	ds_read_b32 v102, v0 offset:9856
	ds_read_b32 v103, v0 offset:9888
	ds_read_b32 v107, v0 offset:10064
	ds_read_b32 v108, v0 offset:10096
	ds_read_b32 v109, v0 offset:10128
	ds_read_b32 v110, v0 offset:10160
	ds_read_b32 v114, v0 offset:10336
	ds_read_b32 v115, v0 offset:10368
	ds_read_b32 v116, v0 offset:10400
	ds_read_b32 v117, v0 offset:10432
	ds_read_b32 v121, v0 offset:10608
	ds_read_b32 v122, v0 offset:10640
	ds_read_b32 v123, v0 offset:10672
	ds_read_b32 v124, v0 offset:10704
	v_fma_f32 v25, -v32, v24, v25
	v_fma_f32 v26, -v36, v24, v26
	v_fma_f32 v27, -v40, v24, v27
	v_fma_f32 v28, -v44, v24, v28
	v_fma_f32 v29, -v48, v24, v29
	v_fma_f32 v30, -v56, v24, v30
	v_fma_f32 v31, -v64, v24, v31
	v_fma_f32 v26, -v37, v25, v26
	v_fma_f32 v27, -v41, v25, v27
	v_fma_f32 v28, -v45, v25, v28
	v_fma_f32 v29, -v49, v25, v29
	v_fma_f32 v30, -v57, v25, v30
	v_fma_f32 v31, -v65, v25, v31
	v_fma_f32 v27, -v42, v26, v27
	v_fma_f32 v28, -v46, v26, v28
	v_fma_f32 v29, -v50, v26, v29
	v_fma_f32 v30, -v58, v26, v30
	v_fma_f32 v31, -v66, v26, v31
	v_fma_f32 v28, -v47, v27, v28
	v_fma_f32 v29, -v51, v27, v29
	v_fma_f32 v30, -v59, v27, v30
	v_fma_f32 v31, -v67, v27, v31
	v_fma_f32 v29, -v52, v28, v29
	v_fma_f32 v30, -v60, v28, v30
	v_fma_f32 v31, -v68, v28, v31
	v_fma_f32 v30, -v61, v29, v30
	v_fma_f32 v31, -v69, v29, v31
	v_fma_f32 v31, -v70, v30, v31
	ds_read_b128 v[32:35], v1 offset:9104
	ds_read_b128 v[36:39], v1 offset:9376
	ds_read_b128 v[40:43], v1 offset:9648
	ds_read_b128 v[44:47], v1 offset:9920
	ds_read_b128 v[48:51], v1 offset:10192
	ds_read_b128 v[52:55], v1 offset:10208
	ds_read_b128 v[56:59], v1 offset:10464
	ds_read_b128 v[60:63], v1 offset:10480
	ds_read_b128 v[64:67], v1 offset:10736
	ds_read_b128 v[68:71], v1 offset:10752
	v_mov_b32_e32 v11, v24
	v_cndmask_b32_e64 v11, v11, v25, s[6:7]
	v_cndmask_b32_e64 v11, v11, v26, s[68:69]
	v_cndmask_b32_e64 v11, v11, v27, s[92:93]
	v_cndmask_b32_e64 v11, v11, v28, s[94:95]
	v_cndmask_b32_e64 v11, v11, v29, s[96:97]
	v_cndmask_b32_e64 v11, v11, v30, s[98:99]
	v_cndmask_b32_e64 v11, v11, v31, s[100:101]
	v_mul_f32_e32 v128, v4, v11
	v_mul_f32_e32 v129, v5, v11
	v_cvt_pk_bf16_f32 v128, v128, v128
	v_cvt_pk_bf16_f32 v129, v129, v129
	ds_write_b16 v2, v128 offset:3456
	ds_write_b16 v3, v129 offset:3456
	s_mov_b32 s91, 0
; #define LAS __attribute__((address_space(3)))
; __device__ __forceinline__ bf16_t f2bf(float f) { return (bf16_t)(cvt_pk_bf16(f, 0.f) & 0xffffu); }
; __device__ __forceinline__ void dn_prep(const Params& p, LAS unsigned char* lds) {
;     ...
;             for (int i = 1; i < 64; ++i) {
; #pragma unroll
;                 for (int j4 = 8; j4 < (i + 3) / 4; ++j4) rhi[j4 - 8] = *(const LAS f32x4*)(Asz + i * 68 + j4 * 4);
;                 if (i + 1 < 64) {
; #pragma unroll
;                     for (int j4 = 0; j4 < ((i + 4) / 4 < 8 ? (i + 4) / 4 : 8); ++j4) rlo[(i + 1) & 1][j4] = *(const LAS f32x4*)(Asz + (i + 1) * 68 + j4 * 4);
;                 }
;                 float a0 = (lane == i) ? 1.f : 0.f, a1 = 0.f, a2 = 0.f, a3 = 0.f;
; #pragma unroll
;                 for (int j4 = 0; j4 < (i + 3) / 4; ++j4) {
;                     const f32x4 av = (j4 < 8) ? rlo[i & 1][j4 & 7] : rhi[(j4 - 8) & 7];
;                     if (j4 * 4 + 0 < i) a0 -= av[0] * T[j4 * 4 + 0];
;                     if (j4 * 4 + 1 < i) a1 -= av[1] * T[j4 * 4 + 1];
;                     if (j4 * 4 + 2 < i) a2 -= av[2] * T[j4 * 4 + 2];
;                     if (j4 * 4 + 3 < i) a3 -= av[3] * T[j4 * 4 + 3];
;                 }
;                 T[i] = (a0 + a1) + (a2 + a3);
;                 tub[i * 72] = f2bf(T[i] * bc); twb[i * 72] = f2bf(T[i] * wcf);
.Lfs_b4:
	s_cmp_gt_u32 s1, 4
	s_cbranch_scc1 .Lfs_z4
	s_waitcnt lgkmcnt(12)
	v_mul_f32_e32 v24, v72, v8
	v_mul_f32_e32 v25, v79, v8
	v_mul_f32_e32 v26, v86, v8
	v_mul_f32_e32 v27, v93, v8
	v_mul_f32_e32 v28, v100, v8
	v_mul_f32_e32 v29, v107, v8
	v_mul_f32_e32 v30, v114, v8
	v_mul_f32_e32 v31, v121, v8
	v_fmac_f32_e32 v24, v73, v9
	v_fmac_f32_e32 v25, v80, v9
	v_fmac_f32_e32 v26, v87, v9
	v_fmac_f32_e32 v27, v94, v9
	v_fmac_f32_e32 v28, v101, v9
	v_fmac_f32_e32 v29, v108, v9
	v_fmac_f32_e32 v30, v115, v9
	v_fmac_f32_e32 v31, v122, v9
	v_fmac_f32_e32 v24, v74, v10
	v_fmac_f32_e32 v25, v81, v10
	v_fmac_f32_e32 v26, v88, v10
	v_fmac_f32_e32 v27, v95, v10
	v_fmac_f32_e32 v28, v102, v10
	v_fmac_f32_e32 v29, v109, v10
	v_fmac_f32_e32 v30, v116, v10
	v_fmac_f32_e32 v31, v123, v10
	v_fmac_f32_e32 v24, v75, v11
	v_fmac_f32_e32 v25, v82, v11
	v_fmac_f32_e32 v26, v89, v11
	v_fmac_f32_e32 v27, v96, v11
	v_fmac_f32_e32 v28, v103, v11
	v_fmac_f32_e32 v29, v110, v11
	v_fmac_f32_e32 v30, v117, v11
	v_fmac_f32_e32 v31, v124, v11
	v_add_f32_dpp v24, v24, v24 quad_perm:[1,0,3,2] row_mask:0xf bank_mask:0xf bound_ctrl:1
	v_add_f32_dpp v25, v25, v25 quad_perm:[1,0,3,2] row_mask:0xf bank_mask:0xf bound_ctrl:1
	v_add_f32_dpp v26, v26, v26 quad_perm:[1,0,3,2] row_mask:0xf bank_mask:0xf bound_ctrl:1
	v_add_f32_dpp v27, v27, v27 quad_perm:[1,0,3,2] row_mask:0xf bank_mask:0xf bound_ctrl:1
	v_add_f32_dpp v28, v28, v28 quad_perm:[1,0,3,2] row_mask:0xf bank_mask:0xf bound_ctrl:1
	v_add_f32_dpp v29, v29, v29 quad_perm:[1,0,3,2] row_mask:0xf bank_mask:0xf bound_ctrl:1
	v_add_f32_dpp v30, v30, v30 quad_perm:[1,0,3,2] row_mask:0xf bank_mask:0xf bound_ctrl:1
	v_add_f32_dpp v31, v31, v31 quad_perm:[1,0,3,2] row_mask:0xf bank_mask:0xf bound_ctrl:1
	v_add_f32_dpp v24, v24, v24 quad_perm:[2,3,0,1] row_mask:0xf bank_mask:0xf bound_ctrl:1
	v_add_f32_dpp v25, v25, v25 quad_perm:[2,3,0,1] row_mask:0xf bank_mask:0xf bound_ctrl:1
	v_add_f32_dpp v26, v26, v26 quad_perm:[2,3,0,1] row_mask:0xf bank_mask:0xf bound_ctrl:1
	v_add_f32_dpp v27, v27, v27 quad_perm:[2,3,0,1] row_mask:0xf bank_mask:0xf bound_ctrl:1
	v_add_f32_dpp v28, v28, v28 quad_perm:[2,3,0,1] row_mask:0xf bank_mask:0xf bound_ctrl:1
	v_add_f32_dpp v29, v29, v29 quad_perm:[2,3,0,1] row_mask:0xf bank_mask:0xf bound_ctrl:1
	v_add_f32_dpp v30, v30, v30 quad_perm:[2,3,0,1] row_mask:0xf bank_mask:0xf bound_ctrl:1
	v_add_f32_dpp v31, v31, v31 quad_perm:[2,3,0,1] row_mask:0xf bank_mask:0xf bound_ctrl:1
	v_add_f32_dpp v24, v24, v24 row_half_mirror row_mask:0xf bank_mask:0xf bound_ctrl:1
	v_add_f32_dpp v25, v25, v25 row_half_mirror row_mask:0xf bank_mask:0xf bound_ctrl:1
	v_add_f32_dpp v26, v26, v26 row_half_mirror row_mask:0xf bank_mask:0xf bound_ctrl:1
	v_add_f32_dpp v27, v27, v27 row_half_mirror row_mask:0xf bank_mask:0xf bound_ctrl:1
	v_add_f32_dpp v28, v28, v28 row_half_mirror row_mask:0xf bank_mask:0xf bound_ctrl:1
	v_add_f32_dpp v29, v29, v29 row_half_mirror row_mask:0xf bank_mask:0xf bound_ctrl:1
	v_add_f32_dpp v30, v30, v30 row_half_mirror row_mask:0xf bank_mask:0xf bound_ctrl:1
	v_add_f32_dpp v31, v31, v31 row_half_mirror row_mask:0xf bank_mask:0xf bound_ctrl:1
	v_fma_f32 v24, v16, s91, -v24
	v_fma_f32 v25, v17, s91, -v25
	v_fma_f32 v26, v18, s91, -v26
	v_fma_f32 v27, v19, s91, -v27
	v_fma_f32 v28, v20, s91, -v28
	v_fma_f32 v29, v21, s91, -v29
	v_fma_f32 v30, v22, s91, -v30
	v_fma_f32 v31, v23, s91, -v31
	s_waitcnt lgkmcnt(0)
	ds_read_b32 v72, v0 offset:10880
	ds_read_b32 v73, v0 offset:10912
	ds_read_b32 v74, v0 offset:10944
	ds_read_b32 v75, v0 offset:10976
	ds_read_b32 v76, v0 offset:11008
	ds_read_b32 v79, v0 offset:11152
	ds_read_b32 v80, v0 offset:11184
	ds_read_b32 v81, v0 offset:11216
	ds_read_b32 v82, v0 offset:11248
	ds_read_b32 v83, v0 offset:11280
	ds_read_b32 v86, v0 offset:11424
	ds_read_b32 v87, v0 offset:11456
	ds_read_b32 v88, v0 offset:11488
	ds_read_b32 v89, v0 offset:11520
	ds_read_b32 v90, v0 offset:11552
	ds_read_b32 v93, v0 offset:11696
	ds_read_b32 v94, v0 offset:11728
	ds_read_b32 v95, v0 offset:11760
	ds_read_b32 v96, v0 offset:11792
	ds_read_b32 v97, v0 offset:11824
	ds_read_b32 v100, v0 offset:11968
	ds_read_b32 v101, v0 offset:12000
	ds_read_b32 v102, v0 offset:12032
	ds_read_b32 v103, v0 offset:12064
	ds_read_b32 v104, v0 offset:12096
	ds_read_b32 v107, v0 offset:12240
	ds_read_b32 v108, v0 offset:12272
	ds_read_b32 v109, v0 offset:12304
	ds_read_b32 v110, v0 offset:12336
	ds_read_b32 v111, v0 offset:12368
	ds_read_b32 v114, v0 offset:12512
	ds_read_b32 v115, v0 offset:12544
	ds_read_b32 v116, v0 offset:12576
	ds_read_b32 v117, v0 offset:12608
	ds_read_b32 v118, v0 offset:12640
	ds_read_b32 v121, v0 offset:12784
	ds_read_b32 v122, v0 offset:12816
	ds_read_b32 v123, v0 offset:12848
	ds_read_b32 v124, v0 offset:12880
	ds_read_b32 v125, v0 offset:12912
	v_fma_f32 v25, -v32, v24, v25
	v_fma_f32 v26, -v36, v24, v26
	v_fma_f32 v27, -v40, v24, v27
	v_fma_f32 v28, -v44, v24, v28
	v_fma_f32 v29, -v48, v24, v29
	v_fma_f32 v30, -v56, v24, v30
	v_fma_f32 v31, -v64, v24, v31
	v_fma_f32 v26, -v37, v25, v26
	v_fma_f32 v27, -v41, v25, v27
	v_fma_f32 v28, -v45, v25, v28
	v_fma_f32 v29, -v49, v25, v29
	v_fma_f32 v30, -v57, v25, v30
	v_fma_f32 v31, -v65, v25, v31
	v_fma_f32 v27, -v42, v26, v27
	v_fma_f32 v28, -v46, v26, v28
	v_fma_f32 v29, -v50, v26, v29
	v_fma_f32 v30, -v58, v26, v30
	v_fma_f32 v31, -v66, v26, v31
	v_fma_f32 v28, -v47, v27, v28
	v_fma_f32 v29, -v51, v27, v29
	v_fma_f32 v30, -v59, v27, v30
	v_fma_f32 v31, -v67, v27, v31
	v_fma_f32 v29, -v52, v28, v29
	v_fma_f32 v30, -v60, v28, v30
	v_fma_f32 v31, -v68, v28, v31
	v_fma_f32 v30, -v61, v29, v30
	v_fma_f32 v31, -v69, v29, v31
	v_fma_f32 v31, -v70, v30, v31
	ds_read_b128 v[32:35], v1 offset:11312
	ds_read_b128 v[36:39], v1 offset:11584
	ds_read_b128 v[40:43], v1 offset:11856
	ds_read_b128 v[44:47], v1 offset:12128
	ds_read_b128 v[48:51], v1 offset:12400
	ds_read_b128 v[52:55], v1 offset:12416
	ds_read_b128 v[56:59], v1 offset:12672
	ds_read_b128 v[60:63], v1 offset:12688
	ds_read_b128 v[64:67], v1 offset:12944
	ds_read_b128 v[68:71], v1 offset:12960
	v_mov_b32_e32 v12, v24
	v_cndmask_b32_e64 v12, v12, v25, s[6:7]
	v_cndmask_b32_e64 v12, v12, v26, s[68:69]
	v_cndmask_b32_e64 v12, v12, v27, s[92:93]
	v_cndmask_b32_e64 v12, v12, v28, s[94:95]
	v_cndmask_b32_e64 v12, v12, v29, s[96:97]
	v_cndmask_b32_e64 v12, v12, v30, s[98:99]
	v_cndmask_b32_e64 v12, v12, v31, s[100:101]
	v_mul_f32_e32 v128, v4, v12
	v_mul_f32_e32 v129, v5, v12
	v_cvt_pk_bf16_f32 v128, v128, v128
	v_cvt_pk_bf16_f32 v129, v129, v129
	ds_write_b16 v2, v128 offset:4608
	ds_write_b16 v3, v129 offset:4608
	s_mov_b32 s91, 0
; #define LAS __attribute__((address_space(3)))
; __device__ __forceinline__ bf16_t f2bf(float f) { return (bf16_t)(cvt_pk_bf16(f, 0.f) & 0xffffu); }
; __device__ __forceinline__ void dn_prep(const Params& p, LAS unsigned char* lds) {
;     ...
;             for (int i = 1; i < 64; ++i) {
; #pragma unroll
;                 for (int j4 = 8; j4 < (i + 3) / 4; ++j4) rhi[j4 - 8] = *(const LAS f32x4*)(Asz + i * 68 + j4 * 4);
;                 if (i + 1 < 64) {
; #pragma unroll
;                     for (int j4 = 0; j4 < ((i + 4) / 4 < 8 ? (i + 4) / 4 : 8); ++j4) rlo[(i + 1) & 1][j4] = *(const LAS f32x4*)(Asz + (i + 1) * 68 + j4 * 4);
;                 }
;                 float a0 = (lane == i) ? 1.f : 0.f, a1 = 0.f, a2 = 0.f, a3 = 0.f;
; #pragma unroll
;                 for (int j4 = 0; j4 < (i + 3) / 4; ++j4) {
;                     const f32x4 av = (j4 < 8) ? rlo[i & 1][j4 & 7] : rhi[(j4 - 8) & 7];
;                     if (j4 * 4 + 0 < i) a0 -= av[0] * T[j4 * 4 + 0];
;                     if (j4 * 4 + 1 < i) a1 -= av[1] * T[j4 * 4 + 1];
;                     if (j4 * 4 + 2 < i) a2 -= av[2] * T[j4 * 4 + 2];
;                     if (j4 * 4 + 3 < i) a3 -= av[3] * T[j4 * 4 + 3];
;                 }
;                 T[i] = (a0 + a1) + (a2 + a3);
;                 tub[i * 72] = f2bf(T[i] * bc); twb[i * 72] = f2bf(T[i] * wcf);
.Lfs_b5:
	s_cmp_gt_u32 s1, 5
	s_cbranch_scc1 .Lfs_z5
	s_waitcnt lgkmcnt(12)
	v_mul_f32_e32 v24, v72, v8
	v_mul_f32_e32 v25, v79, v8
	v_mul_f32_e32 v26, v86, v8
	v_mul_f32_e32 v27, v93, v8
	v_mul_f32_e32 v28, v100, v8
	v_mul_f32_e32 v29, v107, v8
	v_mul_f32_e32 v30, v114, v8
	v_mul_f32_e32 v31, v121, v8
	v_fmac_f32_e32 v24, v73, v9
	v_fmac_f32_e32 v25, v80, v9
	v_fmac_f32_e32 v26, v87, v9
	v_fmac_f32_e32 v27, v94, v9
	v_fmac_f32_e32 v28, v101, v9
	v_fmac_f32_e32 v29, v108, v9
	v_fmac_f32_e32 v30, v115, v9
	v_fmac_f32_e32 v31, v122, v9
	v_fmac_f32_e32 v24, v74, v10
	v_fmac_f32_e32 v25, v81, v10
	v_fmac_f32_e32 v26, v88, v10
	v_fmac_f32_e32 v27, v95, v10
	v_fmac_f32_e32 v28, v102, v10
	v_fmac_f32_e32 v29, v109, v10
	v_fmac_f32_e32 v30, v116, v10
	v_fmac_f32_e32 v31, v123, v10
	v_fmac_f32_e32 v24, v75, v11
	v_fmac_f32_e32 v25, v82, v11
	v_fmac_f32_e32 v26, v89, v11
	v_fmac_f32_e32 v27, v96, v11
	v_fmac_f32_e32 v28, v103, v11
	v_fmac_f32_e32 v29, v110, v11
	v_fmac_f32_e32 v30, v117, v11
	v_fmac_f32_e32 v31, v124, v11
	v_fmac_f32_e32 v24, v76, v12
	v_fmac_f32_e32 v25, v83, v12
	v_fmac_f32_e32 v26, v90, v12
	v_fmac_f32_e32 v27, v97, v12
	v_fmac_f32_e32 v28, v104, v12
	v_fmac_f32_e32 v29, v111, v12
	v_fmac_f32_e32 v30, v118, v12
	v_fmac_f32_e32 v31, v125, v12
	v_add_f32_dpp v24, v24, v24 quad_perm:[1,0,3,2] row_mask:0xf bank_mask:0xf bound_ctrl:1
	v_add_f32_dpp v25, v25, v25 quad_perm:[1,0,3,2] row_mask:0xf bank_mask:0xf bound_ctrl:1
	v_add_f32_dpp v26, v26, v26 quad_perm:[1,0,3,2] row_mask:0xf bank_mask:0xf bound_ctrl:1
	v_add_f32_dpp v27, v27, v27 quad_perm:[1,0,3,2] row_mask:0xf bank_mask:0xf bound_ctrl:1
	v_add_f32_dpp v28, v28, v28 quad_perm:[1,0,3,2] row_mask:0xf bank_mask:0xf bound_ctrl:1
	v_add_f32_dpp v29, v29, v29 quad_perm:[1,0,3,2] row_mask:0xf bank_mask:0xf bound_ctrl:1
	v_add_f32_dpp v30, v30, v30 quad_perm:[1,0,3,2] row_mask:0xf bank_mask:0xf bound_ctrl:1
	v_add_f32_dpp v31, v31, v31 quad_perm:[1,0,3,2] row_mask:0xf bank_mask:0xf bound_ctrl:1
	v_add_f32_dpp v24, v24, v24 quad_perm:[2,3,0,1] row_mask:0xf bank_mask:0xf bound_ctrl:1
	v_add_f32_dpp v25, v25, v25 quad_perm:[2,3,0,1] row_mask:0xf bank_mask:0xf bound_ctrl:1
	v_add_f32_dpp v26, v26, v26 quad_perm:[2,3,0,1] row_mask:0xf bank_mask:0xf bound_ctrl:1
	v_add_f32_dpp v27, v27, v27 quad_perm:[2,3,0,1] row_mask:0xf bank_mask:0xf bound_ctrl:1
	v_add_f32_dpp v28, v28, v28 quad_perm:[2,3,0,1] row_mask:0xf bank_mask:0xf bound_ctrl:1
	v_add_f32_dpp v29, v29, v29 quad_perm:[2,3,0,1] row_mask:0xf bank_mask:0xf bound_ctrl:1
	v_add_f32_dpp v30, v30, v30 quad_perm:[2,3,0,1] row_mask:0xf bank_mask:0xf bound_ctrl:1
	v_add_f32_dpp v31, v31, v31 quad_perm:[2,3,0,1] row_mask:0xf bank_mask:0xf bound_ctrl:1
	v_add_f32_dpp v24, v24, v24 row_half_mirror row_mask:0xf bank_mask:0xf bound_ctrl:1
	v_add_f32_dpp v25, v25, v25 row_half_mirror row_mask:0xf bank_mask:0xf bound_ctrl:1
	v_add_f32_dpp v26, v26, v26 row_half_mirror row_mask:0xf bank_mask:0xf bound_ctrl:1
	v_add_f32_dpp v27, v27, v27 row_half_mirror row_mask:0xf bank_mask:0xf bound_ctrl:1
	v_add_f32_dpp v28, v28, v28 row_half_mirror row_mask:0xf bank_mask:0xf bound_ctrl:1
	v_add_f32_dpp v29, v29, v29 row_half_mirror row_mask:0xf bank_mask:0xf bound_ctrl:1
	v_add_f32_dpp v30, v30, v30 row_half_mirror row_mask:0xf bank_mask:0xf bound_ctrl:1
	v_add_f32_dpp v31, v31, v31 row_half_mirror row_mask:0xf bank_mask:0xf bound_ctrl:1
	v_fma_f32 v24, v16, s91, -v24
	v_fma_f32 v25, v17, s91, -v25
	v_fma_f32 v26, v18, s91, -v26
	v_fma_f32 v27, v19, s91, -v27
	v_fma_f32 v28, v20, s91, -v28
	v_fma_f32 v29, v21, s91, -v29
	v_fma_f32 v30, v22, s91, -v30
	v_fma_f32 v31, v23, s91, -v31
	s_waitcnt lgkmcnt(0)
	ds_read_b32 v72, v0 offset:13056
	ds_read_b32 v73, v0 offset:13088
	ds_read_b32 v74, v0 offset:13120
	ds_read_b32 v75, v0 offset:13152
	ds_read_b32 v76, v0 offset:13184
	ds_read_b32 v77, v0 offset:13216
	ds_read_b32 v79, v0 offset:13328
	ds_read_b32 v80, v0 offset:13360
	ds_read_b32 v81, v0 offset:13392
	ds_read_b32 v82, v0 offset:13424
	ds_read_b32 v83, v0 offset:13456
	ds_read_b32 v84, v0 offset:13488
	ds_read_b32 v86, v0 offset:13600
	ds_read_b32 v87, v0 offset:13632
	ds_read_b32 v88, v0 offset:13664
	ds_read_b32 v89, v0 offset:13696
	ds_read_b32 v90, v0 offset:13728
	ds_read_b32 v91, v0 offset:13760
	ds_read_b32 v93, v0 offset:13872
	ds_read_b32 v94, v0 offset:13904
	ds_read_b32 v95, v0 offset:13936
	ds_read_b32 v96, v0 offset:13968
	ds_read_b32 v97, v0 offset:14000
	ds_read_b32 v98, v0 offset:14032
	ds_read_b32 v100, v0 offset:14144
	ds_read_b32 v101, v0 offset:14176
	ds_read_b32 v102, v0 offset:14208
	ds_read_b32 v103, v0 offset:14240
	ds_read_b32 v104, v0 offset:14272
	ds_read_b32 v105, v0 offset:14304
	ds_read_b32 v107, v0 offset:14416
	ds_read_b32 v108, v0 offset:14448
	ds_read_b32 v109, v0 offset:14480
	ds_read_b32 v110, v0 offset:14512
	ds_read_b32 v111, v0 offset:14544
	ds_read_b32 v112, v0 offset:14576
	ds_read_b32 v114, v0 offset:14688
	ds_read_b32 v115, v0 offset:14720
	ds_read_b32 v116, v0 offset:14752
	ds_read_b32 v117, v0 offset:14784
	ds_read_b32 v118, v0 offset:14816
	ds_read_b32 v119, v0 offset:14848
	ds_read_b32 v121, v0 offset:14960
	ds_read_b32 v122, v0 offset:14992
	ds_read_b32 v123, v0 offset:15024
	ds_read_b32 v124, v0 offset:15056
	ds_read_b32 v125, v0 offset:15088
	ds_read_b32 v126, v0 offset:15120
	v_fma_f32 v25, -v32, v24, v25
	v_fma_f32 v26, -v36, v24, v26
	v_fma_f32 v27, -v40, v24, v27
	v_fma_f32 v28, -v44, v24, v28
	v_fma_f32 v29, -v48, v24, v29
	v_fma_f32 v30, -v56, v24, v30
	v_fma_f32 v31, -v64, v24, v31
	v_fma_f32 v26, -v37, v25, v26
	v_fma_f32 v27, -v41, v25, v27
	v_fma_f32 v28, -v45, v25, v28
	v_fma_f32 v29, -v49, v25, v29
; #define LAS __attribute__((address_space(3)))
; __device__ __forceinline__ bf16_t f2bf(float f) { return (bf16_t)(cvt_pk_bf16(f, 0.f) & 0xffffu); }
; __device__ __forceinline__ void dn_prep(const Params& p, LAS unsigned char* lds) {
;     ...
;             for (int i = 1; i < 64; ++i) {
; #pragma unroll
;                 for (int j4 = 8; j4 < (i + 3) / 4; ++j4) rhi[j4 - 8] = *(const LAS f32x4*)(Asz + i * 68 + j4 * 4);
;                 if (i + 1 < 64) {
; #pragma unroll
;                     for (int j4 = 0; j4 < ((i + 4) / 4 < 8 ? (i + 4) / 4 : 8); ++j4) rlo[(i + 1) & 1][j4] = *(const LAS f32x4*)(Asz + (i + 1) * 68 + j4 * 4);
;                 }
;                 float a0 = (lane == i) ? 1.f : 0.f, a1 = 0.f, a2 = 0.f, a3 = 0.f;
; #pragma unroll
;                 for (int j4 = 0; j4 < (i + 3) / 4; ++j4) {
;                     const f32x4 av = (j4 < 8) ? rlo[i & 1][j4 & 7] : rhi[(j4 - 8) & 7];
;                     if (j4 * 4 + 0 < i) a0 -= av[0] * T[j4 * 4 + 0];
;                     if (j4 * 4 + 1 < i) a1 -= av[1] * T[j4 * 4 + 1];
;                     if (j4 * 4 + 2 < i) a2 -= av[2] * T[j4 * 4 + 2];
;                     if (j4 * 4 + 3 < i) a3 -= av[3] * T[j4 * 4 + 3];
;                 }
;                 T[i] = (a0 + a1) + (a2 + a3);
;                 tub[i * 72] = f2bf(T[i] * bc); twb[i * 72] = f2bf(T[i] * wcf);
	v_fma_f32 v30, -v57, v25, v30
	v_fma_f32 v31, -v65, v25, v31
	v_fma_f32 v27, -v42, v26, v27
	v_fma_f32 v28, -v46, v26, v28
	v_fma_f32 v29, -v50, v26, v29
	v_fma_f32 v30, -v58, v26, v30
	v_fma_f32 v31, -v66, v26, v31
	v_fma_f32 v28, -v47, v27, v28
	v_fma_f32 v29, -v51, v27, v29
	v_fma_f32 v30, -v59, v27, v30
	v_fma_f32 v31, -v67, v27, v31
	v_fma_f32 v29, -v52, v28, v29
	v_fma_f32 v30, -v60, v28, v30
	v_fma_f32 v31, -v68, v28, v31
	v_fma_f32 v30, -v61, v29, v30
	v_fma_f32 v31, -v69, v29, v31
	v_fma_f32 v31, -v70, v30, v31
	ds_read_b128 v[32:35], v1 offset:13520
	ds_read_b128 v[36:39], v1 offset:13792
	ds_read_b128 v[40:43], v1 offset:14064
	ds_read_b128 v[44:47], v1 offset:14336
	ds_read_b128 v[48:51], v1 offset:14608
	ds_read_b128 v[52:55], v1 offset:14624
	ds_read_b128 v[56:59], v1 offset:14880
	ds_read_b128 v[60:63], v1 offset:14896
	ds_read_b128 v[64:67], v1 offset:15152
	ds_read_b128 v[68:71], v1 offset:15168
	v_mov_b32_e32 v13, v24
	v_cndmask_b32_e64 v13, v13, v25, s[6:7]
	v_cndmask_b32_e64 v13, v13, v26, s[68:69]
	v_cndmask_b32_e64 v13, v13, v27, s[92:93]
	v_cndmask_b32_e64 v13, v13, v28, s[94:95]
	v_cndmask_b32_e64 v13, v13, v29, s[96:97]
	v_cndmask_b32_e64 v13, v13, v30, s[98:99]
	v_cndmask_b32_e64 v13, v13, v31, s[100:101]
	v_mul_f32_e32 v128, v4, v13
	v_mul_f32_e32 v129, v5, v13
	v_cvt_pk_bf16_f32 v128, v128, v128
	v_cvt_pk_bf16_f32 v129, v129, v129
	ds_write_b16 v2, v128 offset:5760
	ds_write_b16 v3, v129 offset:5760
	s_mov_b32 s91, 0
.Lfs_b6:
	s_cmp_gt_u32 s1, 6
	s_cbranch_scc1 .Lfs_z6
	s_waitcnt lgkmcnt(12)
	v_mul_f32_e32 v24, v72, v8
	v_mul_f32_e32 v25, v79, v8
	v_mul_f32_e32 v26, v86, v8
	v_mul_f32_e32 v27, v93, v8
	v_mul_f32_e32 v28, v100, v8
	v_mul_f32_e32 v29, v107, v8
	v_mul_f32_e32 v30, v114, v8
	v_mul_f32_e32 v31, v121, v8
	v_fmac_f32_e32 v24, v73, v9
	v_fmac_f32_e32 v25, v80, v9
	v_fmac_f32_e32 v26, v87, v9
	v_fmac_f32_e32 v27, v94, v9
	v_fmac_f32_e32 v28, v101, v9
	v_fmac_f32_e32 v29, v108, v9
	v_fmac_f32_e32 v30, v115, v9
	v_fmac_f32_e32 v31, v122, v9
	v_fmac_f32_e32 v24, v74, v10
	v_fmac_f32_e32 v25, v81, v10
	v_fmac_f32_e32 v26, v88, v10
	v_fmac_f32_e32 v27, v95, v10
	v_fmac_f32_e32 v28, v102, v10
	v_fmac_f32_e32 v29, v109, v10
	v_fmac_f32_e32 v30, v116, v10
	v_fmac_f32_e32 v31, v123, v10
	v_fmac_f32_e32 v24, v75, v11
	v_fmac_f32_e32 v25, v82, v11
	v_fmac_f32_e32 v26, v89, v11
	v_fmac_f32_e32 v27, v96, v11
	v_fmac_f32_e32 v28, v103, v11
	v_fmac_f32_e32 v29, v110, v11
	v_fmac_f32_e32 v30, v117, v11
	v_fmac_f32_e32 v31, v124, v11
	v_fmac_f32_e32 v24, v76, v12
	v_fmac_f32_e32 v25, v83, v12
	v_fmac_f32_e32 v26, v90, v12
	v_fmac_f32_e32 v27, v97, v12
	v_fmac_f32_e32 v28, v104, v12
	v_fmac_f32_e32 v29, v111, v12
	v_fmac_f32_e32 v30, v118, v12
	v_fmac_f32_e32 v31, v125, v12
	v_fmac_f32_e32 v24, v77, v13
	v_fmac_f32_e32 v25, v84, v13
	v_fmac_f32_e32 v26, v91, v13
	v_fmac_f32_e32 v27, v98, v13
	v_fmac_f32_e32 v28, v105, v13
	v_fmac_f32_e32 v29, v112, v13
	v_fmac_f32_e32 v30, v119, v13
	v_fmac_f32_e32 v31, v126, v13
	v_add_f32_dpp v24, v24, v24 quad_perm:[1,0,3,2] row_mask:0xf bank_mask:0xf bound_ctrl:1
	v_add_f32_dpp v25, v25, v25 quad_perm:[1,0,3,2] row_mask:0xf bank_mask:0xf bound_ctrl:1
	v_add_f32_dpp v26, v26, v26 quad_perm:[1,0,3,2] row_mask:0xf bank_mask:0xf bound_ctrl:1
	v_add_f32_dpp v27, v27, v27 quad_perm:[1,0,3,2] row_mask:0xf bank_mask:0xf bound_ctrl:1
	v_add_f32_dpp v28, v28, v28 quad_perm:[1,0,3,2] row_mask:0xf bank_mask:0xf bound_ctrl:1
	v_add_f32_dpp v29, v29, v29 quad_perm:[1,0,3,2] row_mask:0xf bank_mask:0xf bound_ctrl:1
	v_add_f32_dpp v30, v30, v30 quad_perm:[1,0,3,2] row_mask:0xf bank_mask:0xf bound_ctrl:1
	v_add_f32_dpp v31, v31, v31 quad_perm:[1,0,3,2] row_mask:0xf bank_mask:0xf bound_ctrl:1
	v_add_f32_dpp v24, v24, v24 quad_perm:[2,3,0,1] row_mask:0xf bank_mask:0xf bound_ctrl:1
	v_add_f32_dpp v25, v25, v25 quad_perm:[2,3,0,1] row_mask:0xf bank_mask:0xf bound_ctrl:1
	v_add_f32_dpp v26, v26, v26 quad_perm:[2,3,0,1] row_mask:0xf bank_mask:0xf bound_ctrl:1
	v_add_f32_dpp v27, v27, v27 quad_perm:[2,3,0,1] row_mask:0xf bank_mask:0xf bound_ctrl:1
	v_add_f32_dpp v28, v28, v28 quad_perm:[2,3,0,1] row_mask:0xf bank_mask:0xf bound_ctrl:1
	v_add_f32_dpp v29, v29, v29 quad_perm:[2,3,0,1] row_mask:0xf bank_mask:0xf bound_ctrl:1
	v_add_f32_dpp v30, v30, v30 quad_perm:[2,3,0,1] row_mask:0xf bank_mask:0xf bound_ctrl:1
	v_add_f32_dpp v31, v31, v31 quad_perm:[2,3,0,1] row_mask:0xf bank_mask:0xf bound_ctrl:1
	v_add_f32_dpp v24, v24, v24 row_half_mirror row_mask:0xf bank_mask:0xf bound_ctrl:1
	v_add_f32_dpp v25, v25, v25 row_half_mirror row_mask:0xf bank_mask:0xf bound_ctrl:1
	v_add_f32_dpp v26, v26, v26 row_half_mirror row_mask:0xf bank_mask:0xf bound_ctrl:1
	v_add_f32_dpp v27, v27, v27 row_half_mirror row_mask:0xf bank_mask:0xf bound_ctrl:1
	v_add_f32_dpp v28, v28, v28 row_half_mirror row_mask:0xf bank_mask:0xf bound_ctrl:1
	v_add_f32_dpp v29, v29, v29 row_half_mirror row_mask:0xf bank_mask:0xf bound_ctrl:1
	v_add_f32_dpp v30, v30, v30 row_half_mirror row_mask:0xf bank_mask:0xf bound_ctrl:1
	v_add_f32_dpp v31, v31, v31 row_half_mirror row_mask:0xf bank_mask:0xf bound_ctrl:1
	v_fma_f32 v24, v16, s91, -v24
	v_fma_f32 v25, v17, s91, -v25
	v_fma_f32 v26, v18, s91, -v26
	v_fma_f32 v27, v19, s91, -v27
	v_fma_f32 v28, v20, s91, -v28
	v_fma_f32 v29, v21, s91, -v29
	v_fma_f32 v30, v22, s91, -v30
	v_fma_f32 v31, v23, s91, -v31
	s_waitcnt lgkmcnt(0)
; #define LAS __attribute__((address_space(3)))
; __device__ __forceinline__ bf16_t f2bf(float f) { return (bf16_t)(cvt_pk_bf16(f, 0.f) & 0xffffu); }
; __device__ __forceinline__ void dn_prep(const Params& p, LAS unsigned char* lds) {
;     ...
;             for (int i = 1; i < 64; ++i) {
; #pragma unroll
;                 for (int j4 = 8; j4 < (i + 3) / 4; ++j4) rhi[j4 - 8] = *(const LAS f32x4*)(Asz + i * 68 + j4 * 4);
;                 if (i + 1 < 64) {
; #pragma unroll
;                     for (int j4 = 0; j4 < ((i + 4) / 4 < 8 ? (i + 4) / 4 : 8); ++j4) rlo[(i + 1) & 1][j4] = *(const LAS f32x4*)(Asz + (i + 1) * 68 + j4 * 4);
;                 }
;                 float a0 = (lane == i) ? 1.f : 0.f, a1 = 0.f, a2 = 0.f, a3 = 0.f;
; #pragma unroll
;                 for (int j4 = 0; j4 < (i + 3) / 4; ++j4) {
;                     const f32x4 av = (j4 < 8) ? rlo[i & 1][j4 & 7] : rhi[(j4 - 8) & 7];
;                     if (j4 * 4 + 0 < i) a0 -= av[0] * T[j4 * 4 + 0];
;                     if (j4 * 4 + 1 < i) a1 -= av[1] * T[j4 * 4 + 1];
;                     if (j4 * 4 + 2 < i) a2 -= av[2] * T[j4 * 4 + 2];
;                     if (j4 * 4 + 3 < i) a3 -= av[3] * T[j4 * 4 + 3];
;                 }
;                 T[i] = (a0 + a1) + (a2 + a3);
;                 tub[i * 72] = f2bf(T[i] * bc); twb[i * 72] = f2bf(T[i] * wcf);
	ds_read_b32 v72, v0 offset:15232
	ds_read_b32 v73, v0 offset:15264
	ds_read_b32 v74, v0 offset:15296
	ds_read_b32 v75, v0 offset:15328
	ds_read_b32 v76, v0 offset:15360
	ds_read_b32 v77, v0 offset:15392
	ds_read_b32 v78, v0 offset:15424
	ds_read_b32 v79, v0 offset:15504
	ds_read_b32 v80, v0 offset:15536
	ds_read_b32 v81, v0 offset:15568
	ds_read_b32 v82, v0 offset:15600
	ds_read_b32 v83, v0 offset:15632
	ds_read_b32 v84, v0 offset:15664
	ds_read_b32 v85, v0 offset:15696
	ds_read_b32 v86, v0 offset:15776
	ds_read_b32 v87, v0 offset:15808
	ds_read_b32 v88, v0 offset:15840
	ds_read_b32 v89, v0 offset:15872
	ds_read_b32 v90, v0 offset:15904
	ds_read_b32 v91, v0 offset:15936
	ds_read_b32 v92, v0 offset:15968
	ds_read_b32 v93, v0 offset:16048
	ds_read_b32 v94, v0 offset:16080
	ds_read_b32 v95, v0 offset:16112
	ds_read_b32 v96, v0 offset:16144
	ds_read_b32 v97, v0 offset:16176
	ds_read_b32 v98, v0 offset:16208
	ds_read_b32 v99, v0 offset:16240
	ds_read_b32 v100, v0 offset:16320
	ds_read_b32 v101, v0 offset:16352
	ds_read_b32 v102, v0 offset:16384
	ds_read_b32 v103, v0 offset:16416
	ds_read_b32 v104, v0 offset:16448
	ds_read_b32 v105, v0 offset:16480
	ds_read_b32 v106, v0 offset:16512
	ds_read_b32 v107, v0 offset:16592
	ds_read_b32 v108, v0 offset:16624
	ds_read_b32 v109, v0 offset:16656
	ds_read_b32 v110, v0 offset:16688
	ds_read_b32 v111, v0 offset:16720
	ds_read_b32 v112, v0 offset:16752
	ds_read_b32 v113, v0 offset:16784
	ds_read_b32 v114, v0 offset:16864
	ds_read_b32 v115, v0 offset:16896
	ds_read_b32 v116, v0 offset:16928
	ds_read_b32 v117, v0 offset:16960
	ds_read_b32 v118, v0 offset:16992
	ds_read_b32 v119, v0 offset:17024
	ds_read_b32 v120, v0 offset:17056
	ds_read_b32 v121, v0 offset:17136
	ds_read_b32 v122, v0 offset:17168
	ds_read_b32 v123, v0 offset:17200
	ds_read_b32 v124, v0 offset:17232
	ds_read_b32 v125, v0 offset:17264
	ds_read_b32 v126, v0 offset:17296
	ds_read_b32 v127, v0 offset:17328
	v_fma_f32 v25, -v32, v24, v25
	v_fma_f32 v26, -v36, v24, v26
	v_fma_f32 v27, -v40, v24, v27
	v_fma_f32 v28, -v44, v24, v28
	v_fma_f32 v29, -v48, v24, v29
	v_fma_f32 v30, -v56, v24, v30
	v_fma_f32 v31, -v64, v24, v31
	v_fma_f32 v26, -v37, v25, v26
	v_fma_f32 v27, -v41, v25, v27
	v_fma_f32 v28, -v45, v25, v28
	v_fma_f32 v29, -v49, v25, v29
	v_fma_f32 v30, -v57, v25, v30
	v_fma_f32 v31, -v65, v25, v31
	v_fma_f32 v27, -v42, v26, v27
	v_fma_f32 v28, -v46, v26, v28
	v_fma_f32 v29, -v50, v26, v29
	v_fma_f32 v30, -v58, v26, v30
	v_fma_f32 v31, -v66, v26, v31
	v_fma_f32 v28, -v47, v27, v28
	v_fma_f32 v29, -v51, v27, v29
	v_fma_f32 v30, -v59, v27, v30
	v_fma_f32 v31, -v67, v27, v31
	v_fma_f32 v29, -v52, v28, v29
	v_fma_f32 v30, -v60, v28, v30
	v_fma_f32 v31, -v68, v28, v31
	v_fma_f32 v30, -v61, v29, v30
	v_fma_f32 v31, -v69, v29, v31
	v_fma_f32 v31, -v70, v30, v31
	ds_read_b128 v[32:35], v1 offset:15728
	ds_read_b128 v[36:39], v1 offset:16000
	ds_read_b128 v[40:43], v1 offset:16272
	ds_read_b128 v[44:47], v1 offset:16544
	ds_read_b128 v[48:51], v1 offset:16816
	ds_read_b128 v[52:55], v1 offset:16832
	ds_read_b128 v[56:59], v1 offset:17088
	ds_read_b128 v[60:63], v1 offset:17104
	ds_read_b128 v[64:67], v1 offset:17360
	ds_read_b128 v[68:71], v1 offset:17376
	v_mov_b32_e32 v14, v24
	v_cndmask_b32_e64 v14, v14, v25, s[6:7]
	v_cndmask_b32_e64 v14, v14, v26, s[68:69]
	v_cndmask_b32_e64 v14, v14, v27, s[92:93]
	v_cndmask_b32_e64 v14, v14, v28, s[94:95]
	v_cndmask_b32_e64 v14, v14, v29, s[96:97]
	v_cndmask_b32_e64 v14, v14, v30, s[98:99]
	v_cndmask_b32_e64 v14, v14, v31, s[100:101]
	v_mul_f32_e32 v128, v4, v14
	v_mul_f32_e32 v129, v5, v14
	v_cvt_pk_bf16_f32 v128, v128, v128
	v_cvt_pk_bf16_f32 v129, v129, v129
	ds_write_b16 v2, v128 offset:6912
	ds_write_b16 v3, v129 offset:6912
	s_mov_b32 s91, 0
.Lfs_b7:
	s_waitcnt lgkmcnt(12)
	v_mul_f32_e32 v24, v72, v8
	v_mul_f32_e32 v25, v79, v8
	v_mul_f32_e32 v26, v86, v8
	v_mul_f32_e32 v27, v93, v8
	v_mul_f32_e32 v28, v100, v8
	v_mul_f32_e32 v29, v107, v8
	v_mul_f32_e32 v30, v114, v8
	v_mul_f32_e32 v31, v121, v8
	v_fmac_f32_e32 v24, v73, v9
	v_fmac_f32_e32 v25, v80, v9
	v_fmac_f32_e32 v26, v87, v9
	v_fmac_f32_e32 v27, v94, v9
	v_fmac_f32_e32 v28, v101, v9
	v_fmac_f32_e32 v29, v108, v9
	v_fmac_f32_e32 v30, v115, v9
	v_fmac_f32_e32 v31, v122, v9
	v_fmac_f32_e32 v24, v74, v10
	v_fmac_f32_e32 v25, v81, v10
	v_fmac_f32_e32 v26, v88, v10
	v_fmac_f32_e32 v27, v95, v10
	v_fmac_f32_e32 v28, v102, v10
	v_fmac_f32_e32 v29, v109, v10
	v_fmac_f32_e32 v30, v116, v10
	v_fmac_f32_e32 v31, v123, v10
	v_fmac_f32_e32 v24, v75, v11
	v_fmac_f32_e32 v25, v82, v11
	v_fmac_f32_e32 v26, v89, v11
	v_fmac_f32_e32 v27, v96, v11
	v_fmac_f32_e32 v28, v103, v11
	v_fmac_f32_e32 v29, v110, v11
	v_fmac_f32_e32 v30, v117, v11
	v_fmac_f32_e32 v31, v124, v11
	v_fmac_f32_e32 v24, v76, v12
	v_fmac_f32_e32 v25, v83, v12
	v_fmac_f32_e32 v26, v90, v12
	v_fmac_f32_e32 v27, v97, v12
	v_fmac_f32_e32 v28, v104, v12
	v_fmac_f32_e32 v29, v111, v12
	v_fmac_f32_e32 v30, v118, v12
	v_fmac_f32_e32 v31, v125, v12
	v_fmac_f32_e32 v24, v77, v13
	v_fmac_f32_e32 v25, v84, v13
	v_fmac_f32_e32 v26, v91, v13
	v_fmac_f32_e32 v27, v98, v13
	v_fmac_f32_e32 v28, v105, v13
	v_fmac_f32_e32 v29, v112, v13
	v_fmac_f32_e32 v30, v119, v13
	v_fmac_f32_e32 v31, v126, v13
	v_fmac_f32_e32 v24, v78, v14
	v_fmac_f32_e32 v25, v85, v14
	v_fmac_f32_e32 v26, v92, v14
	v_fmac_f32_e32 v27, v99, v14
	v_fmac_f32_e32 v28, v106, v14
	v_fmac_f32_e32 v29, v113, v14
	v_fmac_f32_e32 v30, v120, v14
	v_fmac_f32_e32 v31, v127, v14
	v_add_f32_dpp v24, v24, v24 quad_perm:[1,0,3,2] row_mask:0xf bank_mask:0xf bound_ctrl:1
	v_add_f32_dpp v25, v25, v25 quad_perm:[1,0,3,2] row_mask:0xf bank_mask:0xf bound_ctrl:1
; #define LAS __attribute__((address_space(3)))
; __device__ __forceinline__ bf16_t f2bf(float f) { return (bf16_t)(cvt_pk_bf16(f, 0.f) & 0xffffu); }
; __device__ __forceinline__ void dn_prep(const Params& p, LAS unsigned char* lds) {
;     ...
;             for (int i = 16; i < 64; ++i) { tub[i * 72] = 0; twb[i * 72] = 0; }
;     ...
;             for (int i = 1; i < 64; ++i) {
; #pragma unroll
;                 for (int j4 = 8; j4 < (i + 3) / 4; ++j4) rhi[j4 - 8] = *(const LAS f32x4*)(Asz + i * 68 + j4 * 4);
;                 if (i + 1 < 64) {
; #pragma unroll
;                     for (int j4 = 0; j4 < ((i + 4) / 4 < 8 ? (i + 4) / 4 : 8); ++j4) rlo[(i + 1) & 1][j4] = *(const LAS f32x4*)(Asz + (i + 1) * 68 + j4 * 4);
;                 }
;                 float a0 = (lane == i) ? 1.f : 0.f, a1 = 0.f, a2 = 0.f, a3 = 0.f;
; #pragma unroll
;                 for (int j4 = 0; j4 < (i + 3) / 4; ++j4) {
;                     const f32x4 av = (j4 < 8) ? rlo[i & 1][j4 & 7] : rhi[(j4 - 8) & 7];
;                     if (j4 * 4 + 0 < i) a0 -= av[0] * T[j4 * 4 + 0];
;                     if (j4 * 4 + 1 < i) a1 -= av[1] * T[j4 * 4 + 1];
;                     if (j4 * 4 + 2 < i) a2 -= av[2] * T[j4 * 4 + 2];
;                     if (j4 * 4 + 3 < i) a3 -= av[3] * T[j4 * 4 + 3];
;                 }
;                 T[i] = (a0 + a1) + (a2 + a3);
;                 tub[i * 72] = f2bf(T[i] * bc); twb[i * 72] = f2bf(T[i] * wcf);
	v_add_f32_dpp v26, v26, v26 quad_perm:[1,0,3,2] row_mask:0xf bank_mask:0xf bound_ctrl:1
	v_add_f32_dpp v27, v27, v27 quad_perm:[1,0,3,2] row_mask:0xf bank_mask:0xf bound_ctrl:1
	v_add_f32_dpp v28, v28, v28 quad_perm:[1,0,3,2] row_mask:0xf bank_mask:0xf bound_ctrl:1
	v_add_f32_dpp v29, v29, v29 quad_perm:[1,0,3,2] row_mask:0xf bank_mask:0xf bound_ctrl:1
	v_add_f32_dpp v30, v30, v30 quad_perm:[1,0,3,2] row_mask:0xf bank_mask:0xf bound_ctrl:1
	v_add_f32_dpp v31, v31, v31 quad_perm:[1,0,3,2] row_mask:0xf bank_mask:0xf bound_ctrl:1
	v_add_f32_dpp v24, v24, v24 quad_perm:[2,3,0,1] row_mask:0xf bank_mask:0xf bound_ctrl:1
	v_add_f32_dpp v25, v25, v25 quad_perm:[2,3,0,1] row_mask:0xf bank_mask:0xf bound_ctrl:1
	v_add_f32_dpp v26, v26, v26 quad_perm:[2,3,0,1] row_mask:0xf bank_mask:0xf bound_ctrl:1
	v_add_f32_dpp v27, v27, v27 quad_perm:[2,3,0,1] row_mask:0xf bank_mask:0xf bound_ctrl:1
	v_add_f32_dpp v28, v28, v28 quad_perm:[2,3,0,1] row_mask:0xf bank_mask:0xf bound_ctrl:1
	v_add_f32_dpp v29, v29, v29 quad_perm:[2,3,0,1] row_mask:0xf bank_mask:0xf bound_ctrl:1
	v_add_f32_dpp v30, v30, v30 quad_perm:[2,3,0,1] row_mask:0xf bank_mask:0xf bound_ctrl:1
	v_add_f32_dpp v31, v31, v31 quad_perm:[2,3,0,1] row_mask:0xf bank_mask:0xf bound_ctrl:1
	v_add_f32_dpp v24, v24, v24 row_half_mirror row_mask:0xf bank_mask:0xf bound_ctrl:1
	v_add_f32_dpp v25, v25, v25 row_half_mirror row_mask:0xf bank_mask:0xf bound_ctrl:1
	v_add_f32_dpp v26, v26, v26 row_half_mirror row_mask:0xf bank_mask:0xf bound_ctrl:1
	v_add_f32_dpp v27, v27, v27 row_half_mirror row_mask:0xf bank_mask:0xf bound_ctrl:1
	v_add_f32_dpp v28, v28, v28 row_half_mirror row_mask:0xf bank_mask:0xf bound_ctrl:1
	v_add_f32_dpp v29, v29, v29 row_half_mirror row_mask:0xf bank_mask:0xf bound_ctrl:1
	v_add_f32_dpp v30, v30, v30 row_half_mirror row_mask:0xf bank_mask:0xf bound_ctrl:1
	v_add_f32_dpp v31, v31, v31 row_half_mirror row_mask:0xf bank_mask:0xf bound_ctrl:1
	v_fma_f32 v24, v16, s91, -v24
	v_fma_f32 v25, v17, s91, -v25
	v_fma_f32 v26, v18, s91, -v26
	v_fma_f32 v27, v19, s91, -v27
	v_fma_f32 v28, v20, s91, -v28
	v_fma_f32 v29, v21, s91, -v29
	v_fma_f32 v30, v22, s91, -v30
	v_fma_f32 v31, v23, s91, -v31
	s_waitcnt lgkmcnt(0)
	v_fma_f32 v25, -v32, v24, v25
	v_fma_f32 v26, -v36, v24, v26
	v_fma_f32 v27, -v40, v24, v27
	v_fma_f32 v28, -v44, v24, v28
	v_fma_f32 v29, -v48, v24, v29
	v_fma_f32 v30, -v56, v24, v30
	v_fma_f32 v31, -v64, v24, v31
	v_fma_f32 v26, -v37, v25, v26
	v_fma_f32 v27, -v41, v25, v27
	v_fma_f32 v28, -v45, v25, v28
	v_fma_f32 v29, -v49, v25, v29
	v_fma_f32 v30, -v57, v25, v30
	v_fma_f32 v31, -v65, v25, v31
	v_fma_f32 v27, -v42, v26, v27
	v_fma_f32 v28, -v46, v26, v28
	v_fma_f32 v29, -v50, v26, v29
	v_fma_f32 v30, -v58, v26, v30
	v_fma_f32 v31, -v66, v26, v31
	v_fma_f32 v28, -v47, v27, v28
	v_fma_f32 v29, -v51, v27, v29
	v_fma_f32 v30, -v59, v27, v30
	v_fma_f32 v31, -v67, v27, v31
	v_fma_f32 v29, -v52, v28, v29
	v_fma_f32 v30, -v60, v28, v30
	v_fma_f32 v31, -v68, v28, v31
	v_fma_f32 v30, -v61, v29, v30
	v_fma_f32 v31, -v69, v29, v31
	v_fma_f32 v31, -v70, v30, v31
	v_mov_b32_e32 v15, v24
	v_cndmask_b32_e64 v15, v15, v25, s[6:7]
	v_cndmask_b32_e64 v15, v15, v26, s[68:69]
	v_cndmask_b32_e64 v15, v15, v27, s[92:93]
	v_cndmask_b32_e64 v15, v15, v28, s[94:95]
	v_cndmask_b32_e64 v15, v15, v29, s[96:97]
	v_cndmask_b32_e64 v15, v15, v30, s[98:99]
	v_cndmask_b32_e64 v15, v15, v31, s[100:101]
	v_mul_f32_e32 v128, v4, v15
	v_mul_f32_e32 v129, v5, v15
	v_cvt_pk_bf16_f32 v128, v128, v128
	v_cvt_pk_bf16_f32 v129, v129, v129
	ds_write_b16 v2, v128 offset:8064
	ds_write_b16 v3, v129 offset:8064
	s_mov_b32 s91, 0
	s_branch .LBB0_378
.Lfs_z0:
	s_cmp_eq_u32 s1, 1
	s_cbranch_scc0 .Lfs_zw0
	ds_read_b32 v72, v0 offset:2176
	ds_read_b32 v79, v0 offset:2448
	ds_read_b32 v86, v0 offset:2720
	ds_read_b32 v93, v0 offset:2992
	ds_read_b32 v100, v0 offset:3264
	ds_read_b32 v107, v0 offset:3536
	ds_read_b32 v114, v0 offset:3808
	ds_read_b32 v121, v0 offset:4080
	ds_read_b128 v[32:35], v1 offset:2480
	ds_read_b128 v[36:39], v1 offset:2752
	ds_read_b128 v[40:43], v1 offset:3024
	ds_read_b128 v[44:47], v1 offset:3296
	ds_read_b128 v[48:51], v1 offset:3568
	ds_read_b128 v[52:55], v1 offset:3584
	ds_read_b128 v[56:59], v1 offset:3840
	ds_read_b128 v[60:63], v1 offset:3856
	ds_read_b128 v[64:67], v1 offset:4112
	ds_read_b128 v[68:71], v1 offset:4128
.Lfs_zw0:
	ds_write_b16 v2, v6 offset:0
	ds_write_b16 v3, v6 offset:0
	s_branch .Lfs_b1
.Lfs_z1:
	s_cmp_eq_u32 s1, 2
	s_cbranch_scc0 .Lfs_zw1
	ds_read_b32 v72, v0 offset:4352
	ds_read_b32 v73, v0 offset:4384
	ds_read_b32 v79, v0 offset:4624
	ds_read_b32 v80, v0 offset:4656
	ds_read_b32 v86, v0 offset:4896
	ds_read_b32 v87, v0 offset:4928
	ds_read_b32 v93, v0 offset:5168
	ds_read_b32 v94, v0 offset:5200
	ds_read_b32 v100, v0 offset:5440
	ds_read_b32 v101, v0 offset:5472
	ds_read_b32 v107, v0 offset:5712
	ds_read_b32 v108, v0 offset:5744
	ds_read_b32 v114, v0 offset:5984
	ds_read_b32 v115, v0 offset:6016
	ds_read_b32 v121, v0 offset:6256
	ds_read_b32 v122, v0 offset:6288
	ds_read_b128 v[32:35], v1 offset:4688
	ds_read_b128 v[36:39], v1 offset:4960
	ds_read_b128 v[40:43], v1 offset:5232
	ds_read_b128 v[44:47], v1 offset:5504
	ds_read_b128 v[48:51], v1 offset:5776
	ds_read_b128 v[52:55], v1 offset:5792
	ds_read_b128 v[56:59], v1 offset:6048
	ds_read_b128 v[60:63], v1 offset:6064
	ds_read_b128 v[64:67], v1 offset:6320
	ds_read_b128 v[68:71], v1 offset:6336
.Lfs_zw1:
	ds_write_b16 v2, v6 offset:1152
	ds_write_b16 v3, v6 offset:1152
	s_branch .Lfs_b2
; #define LAS __attribute__((address_space(3)))
; __device__ __forceinline__ bf16_t f2bf(float f) { return (bf16_t)(cvt_pk_bf16(f, 0.f) & 0xffffu); }
; __device__ __forceinline__ void dn_prep(const Params& p, LAS unsigned char* lds) {
;     ...
;             for (int i = 1; i < 64; ++i) {
; #pragma unroll
;                 for (int j4 = 8; j4 < (i + 3) / 4; ++j4) rhi[j4 - 8] = *(const LAS f32x4*)(Asz + i * 68 + j4 * 4);
;                 if (i + 1 < 64) {
; #pragma unroll
;                     for (int j4 = 0; j4 < ((i + 4) / 4 < 8 ? (i + 4) / 4 : 8); ++j4) rlo[(i + 1) & 1][j4] = *(const LAS f32x4*)(Asz + (i + 1) * 68 + j4 * 4);
;                 }
;                 float a0 = (lane == i) ? 1.f : 0.f, a1 = 0.f, a2 = 0.f, a3 = 0.f;
; #pragma unroll
;                 for (int j4 = 0; j4 < (i + 3) / 4; ++j4) {
;                     const f32x4 av = (j4 < 8) ? rlo[i & 1][j4 & 7] : rhi[(j4 - 8) & 7];
;                     if (j4 * 4 + 0 < i) a0 -= av[0] * T[j4 * 4 + 0];
;                     if (j4 * 4 + 1 < i) a1 -= av[1] * T[j4 * 4 + 1];
;                     if (j4 * 4 + 2 < i) a2 -= av[2] * T[j4 * 4 + 2];
;                     if (j4 * 4 + 3 < i) a3 -= av[3] * T[j4 * 4 + 3];
;                 }
;                 T[i] = (a0 + a1) + (a2 + a3);
;                 tub[i * 72] = f2bf(T[i] * bc); twb[i * 72] = f2bf(T[i] * wcf);
.Lfs_z2:
	s_cmp_eq_u32 s1, 3
	s_cbranch_scc0 .Lfs_zw2
	ds_read_b32 v72, v0 offset:6528
	ds_read_b32 v73, v0 offset:6560
	ds_read_b32 v74, v0 offset:6592
	ds_read_b32 v79, v0 offset:6800
	ds_read_b32 v80, v0 offset:6832
	ds_read_b32 v81, v0 offset:6864
	ds_read_b32 v86, v0 offset:7072
	ds_read_b32 v87, v0 offset:7104
	ds_read_b32 v88, v0 offset:7136
	ds_read_b32 v93, v0 offset:7344
	ds_read_b32 v94, v0 offset:7376
	ds_read_b32 v95, v0 offset:7408
	ds_read_b32 v100, v0 offset:7616
	ds_read_b32 v101, v0 offset:7648
	ds_read_b32 v102, v0 offset:7680
	ds_read_b32 v107, v0 offset:7888
	ds_read_b32 v108, v0 offset:7920
	ds_read_b32 v109, v0 offset:7952
	ds_read_b32 v114, v0 offset:8160
	ds_read_b32 v115, v0 offset:8192
	ds_read_b32 v116, v0 offset:8224
	ds_read_b32 v121, v0 offset:8432
	ds_read_b32 v122, v0 offset:8464
	ds_read_b32 v123, v0 offset:8496
	ds_read_b128 v[32:35], v1 offset:6896
	ds_read_b128 v[36:39], v1 offset:7168
	ds_read_b128 v[40:43], v1 offset:7440
	ds_read_b128 v[44:47], v1 offset:7712
	ds_read_b128 v[48:51], v1 offset:7984
	ds_read_b128 v[52:55], v1 offset:8000
	ds_read_b128 v[56:59], v1 offset:8256
	ds_read_b128 v[60:63], v1 offset:8272
	ds_read_b128 v[64:67], v1 offset:8528
	ds_read_b128 v[68:71], v1 offset:8544
.Lfs_zw2:
	ds_write_b16 v2, v6 offset:2304
	ds_write_b16 v3, v6 offset:2304
	s_branch .Lfs_b3
.Lfs_z3:
	s_cmp_eq_u32 s1, 4
	s_cbranch_scc0 .Lfs_zw3
	ds_read_b32 v72, v0 offset:8704
	ds_read_b32 v73, v0 offset:8736
	ds_read_b32 v74, v0 offset:8768
	ds_read_b32 v75, v0 offset:8800
	ds_read_b32 v79, v0 offset:8976
	ds_read_b32 v80, v0 offset:9008
	ds_read_b32 v81, v0 offset:9040
	ds_read_b32 v82, v0 offset:9072
	ds_read_b32 v86, v0 offset:9248
	ds_read_b32 v87, v0 offset:9280
	ds_read_b32 v88, v0 offset:9312
	ds_read_b32 v89, v0 offset:9344
	ds_read_b32 v93, v0 offset:9520
	ds_read_b32 v94, v0 offset:9552
	ds_read_b32 v95, v0 offset:9584
	ds_read_b32 v96, v0 offset:9616
	ds_read_b32 v100, v0 offset:9792
	ds_read_b32 v101, v0 offset:9824
	ds_read_b32 v102, v0 offset:9856
	ds_read_b32 v103, v0 offset:9888
	ds_read_b32 v107, v0 offset:10064
	ds_read_b32 v108, v0 offset:10096
	ds_read_b32 v109, v0 offset:10128
	ds_read_b32 v110, v0 offset:10160
	ds_read_b32 v114, v0 offset:10336
	ds_read_b32 v115, v0 offset:10368
	ds_read_b32 v116, v0 offset:10400
	ds_read_b32 v117, v0 offset:10432
	ds_read_b32 v121, v0 offset:10608
	ds_read_b32 v122, v0 offset:10640
	ds_read_b32 v123, v0 offset:10672
	ds_read_b32 v124, v0 offset:10704
	ds_read_b128 v[32:35], v1 offset:9104
	ds_read_b128 v[36:39], v1 offset:9376
	ds_read_b128 v[40:43], v1 offset:9648
	ds_read_b128 v[44:47], v1 offset:9920
	ds_read_b128 v[48:51], v1 offset:10192
	ds_read_b128 v[52:55], v1 offset:10208
	ds_read_b128 v[56:59], v1 offset:10464
	ds_read_b128 v[60:63], v1 offset:10480
	ds_read_b128 v[64:67], v1 offset:10736
	ds_read_b128 v[68:71], v1 offset:10752
.Lfs_zw3:
	ds_write_b16 v2, v6 offset:3456
	ds_write_b16 v3, v6 offset:3456
	s_branch .Lfs_b4
.Lfs_z4:
	s_cmp_eq_u32 s1, 5
	s_cbranch_scc0 .Lfs_zw4
	ds_read_b32 v72, v0 offset:10880
	ds_read_b32 v73, v0 offset:10912
	ds_read_b32 v74, v0 offset:10944
	ds_read_b32 v75, v0 offset:10976
	ds_read_b32 v76, v0 offset:11008
	ds_read_b32 v79, v0 offset:11152
	ds_read_b32 v80, v0 offset:11184
	ds_read_b32 v81, v0 offset:11216
	ds_read_b32 v82, v0 offset:11248
	ds_read_b32 v83, v0 offset:11280
	ds_read_b32 v86, v0 offset:11424
	ds_read_b32 v87, v0 offset:11456
	ds_read_b32 v88, v0 offset:11488
	ds_read_b32 v89, v0 offset:11520
	ds_read_b32 v90, v0 offset:11552
	ds_read_b32 v93, v0 offset:11696
	ds_read_b32 v94, v0 offset:11728
	ds_read_b32 v95, v0 offset:11760
	ds_read_b32 v96, v0 offset:11792
	ds_read_b32 v97, v0 offset:11824
	ds_read_b32 v100, v0 offset:11968
	ds_read_b32 v101, v0 offset:12000
	ds_read_b32 v102, v0 offset:12032
	ds_read_b32 v103, v0 offset:12064
	ds_read_b32 v104, v0 offset:12096
	ds_read_b32 v107, v0 offset:12240
	ds_read_b32 v108, v0 offset:12272
	ds_read_b32 v109, v0 offset:12304
	ds_read_b32 v110, v0 offset:12336
	ds_read_b32 v111, v0 offset:12368
	ds_read_b32 v114, v0 offset:12512
	ds_read_b32 v115, v0 offset:12544
	ds_read_b32 v116, v0 offset:12576
	ds_read_b32 v117, v0 offset:12608
	ds_read_b32 v118, v0 offset:12640
	ds_read_b32 v121, v0 offset:12784
	ds_read_b32 v122, v0 offset:12816
	ds_read_b32 v123, v0 offset:12848
	ds_read_b32 v124, v0 offset:12880
	ds_read_b32 v125, v0 offset:12912
	ds_read_b128 v[32:35], v1 offset:11312
	ds_read_b128 v[36:39], v1 offset:11584
	ds_read_b128 v[40:43], v1 offset:11856
	ds_read_b128 v[44:47], v1 offset:12128
	ds_read_b128 v[48:51], v1 offset:12400
	ds_read_b128 v[52:55], v1 offset:12416
	ds_read_b128 v[56:59], v1 offset:12672
	ds_read_b128 v[60:63], v1 offset:12688
	ds_read_b128 v[64:67], v1 offset:12944
	ds_read_b128 v[68:71], v1 offset:12960
; #define LAS __attribute__((address_space(3)))
; __device__ __forceinline__ bf16_t f2bf(float f) { return (bf16_t)(cvt_pk_bf16(f, 0.f) & 0xffffu); }
; __device__ __forceinline__ void dn_prep(const Params& p, LAS unsigned char* lds) {
;     ...
;             for (int i = 1; i < 64; ++i) {
; #pragma unroll
;                 for (int j4 = 8; j4 < (i + 3) / 4; ++j4) rhi[j4 - 8] = *(const LAS f32x4*)(Asz + i * 68 + j4 * 4);
;                 if (i + 1 < 64) {
; #pragma unroll
;                     for (int j4 = 0; j4 < ((i + 4) / 4 < 8 ? (i + 4) / 4 : 8); ++j4) rlo[(i + 1) & 1][j4] = *(const LAS f32x4*)(Asz + (i + 1) * 68 + j4 * 4);
;                 }
;                 float a0 = (lane == i) ? 1.f : 0.f, a1 = 0.f, a2 = 0.f, a3 = 0.f;
; #pragma unroll
;                 for (int j4 = 0; j4 < (i + 3) / 4; ++j4) {
;                     const f32x4 av = (j4 < 8) ? rlo[i & 1][j4 & 7] : rhi[(j4 - 8) & 7];
;                     if (j4 * 4 + 0 < i) a0 -= av[0] * T[j4 * 4 + 0];
;                     if (j4 * 4 + 1 < i) a1 -= av[1] * T[j4 * 4 + 1];
;                     if (j4 * 4 + 2 < i) a2 -= av[2] * T[j4 * 4 + 2];
;                     if (j4 * 4 + 3 < i) a3 -= av[3] * T[j4 * 4 + 3];
;                 }
;                 T[i] = (a0 + a1) + (a2 + a3);
;                 tub[i * 72] = f2bf(T[i] * bc); twb[i * 72] = f2bf(T[i] * wcf);
.Lfs_zw4:
	ds_write_b16 v2, v6 offset:4608
	ds_write_b16 v3, v6 offset:4608
	s_branch .Lfs_b5
.Lfs_z5:
	s_cmp_eq_u32 s1, 6
	s_cbranch_scc0 .Lfs_zw5
	ds_read_b32 v72, v0 offset:13056
	ds_read_b32 v73, v0 offset:13088
	ds_read_b32 v74, v0 offset:13120
	ds_read_b32 v75, v0 offset:13152
	ds_read_b32 v76, v0 offset:13184
	ds_read_b32 v77, v0 offset:13216
	ds_read_b32 v79, v0 offset:13328
	ds_read_b32 v80, v0 offset:13360
	ds_read_b32 v81, v0 offset:13392
	ds_read_b32 v82, v0 offset:13424
	ds_read_b32 v83, v0 offset:13456
	ds_read_b32 v84, v0 offset:13488
	ds_read_b32 v86, v0 offset:13600
	ds_read_b32 v87, v0 offset:13632
	ds_read_b32 v88, v0 offset:13664
	ds_read_b32 v89, v0 offset:13696
	ds_read_b32 v90, v0 offset:13728
	ds_read_b32 v91, v0 offset:13760
	ds_read_b32 v93, v0 offset:13872
	ds_read_b32 v94, v0 offset:13904
	ds_read_b32 v95, v0 offset:13936
	ds_read_b32 v96, v0 offset:13968
	ds_read_b32 v97, v0 offset:14000
	ds_read_b32 v98, v0 offset:14032
	ds_read_b32 v100, v0 offset:14144
	ds_read_b32 v101, v0 offset:14176
	ds_read_b32 v102, v0 offset:14208
	ds_read_b32 v103, v0 offset:14240
	ds_read_b32 v104, v0 offset:14272
	ds_read_b32 v105, v0 offset:14304
	ds_read_b32 v107, v0 offset:14416
	ds_read_b32 v108, v0 offset:14448
	ds_read_b32 v109, v0 offset:14480
	ds_read_b32 v110, v0 offset:14512
	ds_read_b32 v111, v0 offset:14544
	ds_read_b32 v112, v0 offset:14576
	ds_read_b32 v114, v0 offset:14688
	ds_read_b32 v115, v0 offset:14720
	ds_read_b32 v116, v0 offset:14752
	ds_read_b32 v117, v0 offset:14784
	ds_read_b32 v118, v0 offset:14816
	ds_read_b32 v119, v0 offset:14848
	ds_read_b32 v121, v0 offset:14960
	ds_read_b32 v122, v0 offset:14992
	ds_read_b32 v123, v0 offset:15024
	ds_read_b32 v124, v0 offset:15056
	ds_read_b32 v125, v0 offset:15088
	ds_read_b32 v126, v0 offset:15120
	ds_read_b128 v[32:35], v1 offset:13520
	ds_read_b128 v[36:39], v1 offset:13792
	ds_read_b128 v[40:43], v1 offset:14064
	ds_read_b128 v[44:47], v1 offset:14336
	ds_read_b128 v[48:51], v1 offset:14608
	ds_read_b128 v[52:55], v1 offset:14624
	ds_read_b128 v[56:59], v1 offset:14880
	ds_read_b128 v[60:63], v1 offset:14896
	ds_read_b128 v[64:67], v1 offset:15152
	ds_read_b128 v[68:71], v1 offset:15168
.Lfs_zw5:
	ds_write_b16 v2, v6 offset:5760
	ds_write_b16 v3, v6 offset:5760
	s_branch .Lfs_b6
.Lfs_z6:
	s_cmp_eq_u32 s1, 7
	s_cbranch_scc0 .Lfs_zw6
	ds_read_b32 v72, v0 offset:15232
	ds_read_b32 v73, v0 offset:15264
	ds_read_b32 v74, v0 offset:15296
	ds_read_b32 v75, v0 offset:15328
	ds_read_b32 v76, v0 offset:15360
	ds_read_b32 v77, v0 offset:15392
	ds_read_b32 v78, v0 offset:15424
	ds_read_b32 v79, v0 offset:15504
	ds_read_b32 v80, v0 offset:15536
	ds_read_b32 v81, v0 offset:15568
	ds_read_b32 v82, v0 offset:15600
	ds_read_b32 v83, v0 offset:15632
	ds_read_b32 v84, v0 offset:15664
	ds_read_b32 v85, v0 offset:15696
	ds_read_b32 v86, v0 offset:15776
	ds_read_b32 v87, v0 offset:15808
	ds_read_b32 v88, v0 offset:15840
	ds_read_b32 v89, v0 offset:15872
	ds_read_b32 v90, v0 offset:15904
	ds_read_b32 v91, v0 offset:15936
	ds_read_b32 v92, v0 offset:15968
	ds_read_b32 v93, v0 offset:16048
	ds_read_b32 v94, v0 offset:16080
	ds_read_b32 v95, v0 offset:16112
	ds_read_b32 v96, v0 offset:16144
	ds_read_b32 v97, v0 offset:16176
	ds_read_b32 v98, v0 offset:16208
	ds_read_b32 v99, v0 offset:16240
	ds_read_b32 v100, v0 offset:16320
	ds_read_b32 v101, v0 offset:16352
	ds_read_b32 v102, v0 offset:16384
	ds_read_b32 v103, v0 offset:16416
	ds_read_b32 v104, v0 offset:16448
	ds_read_b32 v105, v0 offset:16480
	ds_read_b32 v106, v0 offset:16512
	ds_read_b32 v107, v0 offset:16592
	ds_read_b32 v108, v0 offset:16624
	ds_read_b32 v109, v0 offset:16656
	ds_read_b32 v110, v0 offset:16688
	ds_read_b32 v111, v0 offset:16720
	ds_read_b32 v112, v0 offset:16752
	ds_read_b32 v113, v0 offset:16784
	ds_read_b32 v114, v0 offset:16864
	ds_read_b32 v115, v0 offset:16896
	ds_read_b32 v116, v0 offset:16928
	ds_read_b32 v117, v0 offset:16960
	ds_read_b32 v118, v0 offset:16992
	ds_read_b32 v119, v0 offset:17024
	ds_read_b32 v120, v0 offset:17056
	ds_read_b32 v121, v0 offset:17136
	ds_read_b32 v122, v0 offset:17168
	ds_read_b32 v123, v0 offset:17200
	ds_read_b32 v124, v0 offset:17232
	ds_read_b32 v125, v0 offset:17264
	ds_read_b32 v126, v0 offset:17296
	ds_read_b32 v127, v0 offset:17328
	ds_read_b128 v[32:35], v1 offset:15728
	ds_read_b128 v[36:39], v1 offset:16000
	ds_read_b128 v[40:43], v1 offset:16272
	ds_read_b128 v[44:47], v1 offset:16544
	ds_read_b128 v[48:51], v1 offset:16816
	ds_read_b128 v[52:55], v1 offset:16832
	ds_read_b128 v[56:59], v1 offset:17088
	ds_read_b128 v[60:63], v1 offset:17104
	ds_read_b128 v[64:67], v1 offset:17360
	ds_read_b128 v[68:71], v1 offset:17376
.Lfs_zw6:
	ds_write_b16 v2, v6 offset:6912
	ds_write_b16 v3, v6 offset:6912
	s_branch .Lfs_b7

; __global__ void __launch_bounds__(512, 2) mega(Params p) {
;     extern __shared__ __attribute__((aligned(16))) unsigned char lds[];
	.amdhsa_kernel _Z4mega6Params
		.amdhsa_group_segment_fixed_size 0
		.amdhsa_private_segment_fixed_size 0
		.amdhsa_kernarg_size 456
		.amdhsa_user_sgpr_count 2
		.amdhsa_user_sgpr_dispatch_ptr 0
		.amdhsa_user_sgpr_queue_ptr 0
		.amdhsa_user_sgpr_kernarg_segment_ptr 1
		.amdhsa_user_sgpr_dispatch_id 0
		.amdhsa_user_sgpr_kernarg_preload_length 0
		.amdhsa_user_sgpr_kernarg_preload_offset 0
		.amdhsa_user_sgpr_private_segment_size 0
		.amdhsa_uses_dynamic_stack 0
		.amdhsa_enable_private_segment 0
		.amdhsa_system_sgpr_workgroup_id_x 1
		.amdhsa_system_sgpr_workgroup_id_y 0
		.amdhsa_system_sgpr_workgroup_id_z 0
		.amdhsa_system_sgpr_workgroup_info 0
		.amdhsa_system_vgpr_workitem_id 2
		.amdhsa_next_free_vgpr 249
		.amdhsa_next_free_sgpr 102
		.amdhsa_accum_offset 252
		.amdhsa_reserve_vcc 1
		.amdhsa_float_round_mode_32 0
		.amdhsa_float_round_mode_16_64 0
		.amdhsa_float_denorm_mode_32 3
		.amdhsa_float_denorm_mode_16_64 3
		.amdhsa_dx10_clamp 1
		.amdhsa_ieee_mode 1
		.amdhsa_fp16_overflow 0
		.amdhsa_tg_split 0
		.amdhsa_exception_fp_ieee_invalid_op 0
		.amdhsa_exception_fp_denorm_src 0
		.amdhsa_exception_fp_ieee_div_zero 0
		.amdhsa_exception_fp_ieee_overflow 0
		.amdhsa_exception_fp_ieee_underflow 0
		.amdhsa_exception_fp_ieee_inexact 0
		.amdhsa_exception_int_div_zero 0
	.end_amdhsa_kernel

amdhsa.kernels:
  - .agpr_count:     0
    .args:
      - .offset:         0
        .size:           200
        .value_kind:     by_value
      - .offset:         200
        .size:           4
        .value_kind:     hidden_block_count_x
      - .offset:         204
        .size:           4
        .value_kind:     hidden_block_count_y
      - .offset:         208
        .size:           4
        .value_kind:     hidden_block_count_z
      - .offset:         212
        .size:           2
        .value_kind:     hidden_group_size_x
      - .offset:         214
        .size:           2
        .value_kind:     hidden_group_size_y
      - .offset:         216
        .size:           2
        .value_kind:     hidden_group_size_z
      - .offset:         218
        .size:           2
        .value_kind:     hidden_remainder_x
      - .offset:         220
        .size:           2
        .value_kind:     hidden_remainder_y
      - .offset:         222
        .size:           2
        .value_kind:     hidden_remainder_z
      - .offset:         240
        .size:           8
        .value_kind:     hidden_global_offset_x
      - .offset:         248
        .size:           8
        .value_kind:     hidden_global_offset_y
      - .offset:         256
        .size:           8
        .value_kind:     hidden_global_offset_z
      - .offset:         264
        .size:           2
        .value_kind:     hidden_grid_dims
      - .offset:         288
        .size:           8
        .value_kind:     hidden_multigrid_sync_arg
      - .offset:         320
        .size:           4
        .value_kind:     hidden_dynamic_lds_size
    .group_segment_fixed_size: 0
    .kernarg_segment_align: 8
    .kernarg_segment_size: 456
    .language:       OpenCL C
    .language_version:
      - 2
      - 0
    .max_flat_workgroup_size: 512
    .name:           _Z4mega6Params
    .private_segment_fixed_size: 0
    .sgpr_count:     108
    .sgpr_spill_count: 26
    .symbol:         _Z4mega6Params.kd
    .uniform_work_group_size: 1
    .uses_dynamic_stack: false
    .vgpr_count:     249
    .vgpr_spill_count: 0
    .wavefront_size: 64
